# s_setprio 3 while a wave runs the hand-written ffup / ev_in / odin epilogues, back to 0 at the next K-loop
# baseline (speedup 1.0000x reference)
.LBB0_260:
	s_mul_hi_i32 s0, s23, 0x2aaaaaab
	s_lshr_b32 s1, s0, 31
	s_ashr_i32 s4, s0, 4
	s_add_i32 s4, s4, s1
	s_mul_i32 s0, s4, 0x60
	s_sub_i32 s0, s23, s0
	s_lshl_b32 s13, s0, 7
	s_lshl_b32 s14, s4, 7
	s_setprio 0
	v_lshl_or_b32 v64, v183, 3, v191
	v_and_b32_e32 v65, 63, v64
	v_lshrrev_b32_e32 v66, 3, v65
	v_lshrrev_b32_e32 v67, 4, v65
	v_xor_b32_e32 v67, v67, v65
	v_and_b32_e32 v67, 7, v67
	v_lshlrev_b32_e32 v67, 4, v67
	s_movk_i32 s99, 0x800
	v_mad_u32_u24 v112, v66, s99, v67
	v_xor_b32_e32 v68, 64, v112
	v_add_u32_e32 v113, 0x3c00, v68
	v_add_u32_e32 v114, 0x7800, v112
	v_add_u32_e32 v115, 0xb400, v68
	v_add_u32_e32 v116, 0x10000, v112
	v_add_u32_e32 v117, 0x13c00, v68
	v_add_u32_e32 v118, 0x17800, v112
	v_add_u32_e32 v119, 0x1b400, v68
	v_and_b32_e32 v69, 31, v64
	v_bfe_u32 v70, v64, 5, 1
	v_bfe_u32 v71, v64, 1, 3
	v_xor_b32_e32 v71, v71, v70
	v_lshlrev_b32_e32 v71, 4, v71
	v_bfe_u32 v72, v64, 7, 1
	v_lshl_or_b32 v72, v72, 6, v69
	v_lshl_add_u32 v120, v72, 7, v71
	v_bfe_u32 v73, v64, 6, 1
	v_lshl_or_b32 v73, v73, 6, v69
	v_lshl_add_u32 v124, v73, 7, v71
	v_add_u32_e32 v124, 0x4000, v124
	v_xor_b32_e32 v121, 32, v120
	v_xor_b32_e32 v125, 32, v124
	v_xor_b32_e32 v122, 64, v120
	v_xor_b32_e32 v126, 64, v124
	v_xor_b32_e32 v123, 96, v120
	v_xor_b32_e32 v127, 96, v124
	v_lshrrev_b32_e32 v74, 6, v64
	s_nop 0
	v_readfirstlane_b32 s100, v74
	s_nop 3
	s_lshl_b32 s98, s100, 13
	s_mov_b32 s101, 0x0
	s_mov_b32 s99, s14
	s_cmp_lt_u32 s100, 2
	s_cmov_b32 s101, 0xb171900
	s_cmov_b32 s99, s13
	s_and_b32 s100, s100, 1
	s_lshl_b32 s100, s100, 6
	s_add_u32 s99, s99, s100
	s_mul_i32 s99, s99, 0x800
	s_add_u32 s99, s99, s101
	s_add_u32 s0, s90, s99
	s_addc_u32 s1, s91, 0
	v_readlane_b32 s99, v251, 0
	s_cmp_lg_u32 s99, 0
	s_cbranch_scc1 .Lg1_pref
	s_add_u32 m0, s98, 0x0
	s_nop 0
	global_load_lds_dwordx4 v112, s[0:1] offset:0
	global_load_lds_dwordx4 v113, s[0:1] offset:1024
	global_load_lds_dwordx4 v114, s[0:1] offset:2048
	global_load_lds_dwordx4 v115, s[0:1] offset:3072
	s_add_u32 m0, s98, 0x1000
	s_nop 0
	global_load_lds_dwordx4 v116, s[0:1] offset:0
	global_load_lds_dwordx4 v117, s[0:1] offset:1024
	global_load_lds_dwordx4 v118, s[0:1] offset:2048
	global_load_lds_dwordx4 v119, s[0:1] offset:3072
	s_add_u32 s0, s0, 0x80
	s_addc_u32 s1, s1, 0
	s_add_u32 m0, s98, 0x8000
	s_nop 0
	global_load_lds_dwordx4 v112, s[0:1] offset:0
	global_load_lds_dwordx4 v113, s[0:1] offset:1024
	global_load_lds_dwordx4 v114, s[0:1] offset:2048
	global_load_lds_dwordx4 v115, s[0:1] offset:3072
	s_add_u32 m0, s98, 0x9000
	s_nop 0
	global_load_lds_dwordx4 v116, s[0:1] offset:0
	global_load_lds_dwordx4 v117, s[0:1] offset:1024
	global_load_lds_dwordx4 v118, s[0:1] offset:2048
	global_load_lds_dwordx4 v119, s[0:1] offset:3072
	s_add_u32 s0, s0, 0x80
	s_addc_u32 s1, s1, 0
	s_mov_b32 s101, 0
	s_branch .Lg1_prol

.LBB0_268:
	s_setprio 3
	s_lshr_b32 s24, s14, 9
	v_lshl_or_b32 v116, v183, 3, v191
	v_lshrrev_b32_e32 v117, 6, v116
	v_and_b32_e32 v118, 63, v116
	v_lshlrev_b32_e32 v113, 11, v117
	v_add_u32_e32 v113, 0x10000, v113
	v_readfirstlane_b32 s0, v117
	v_and_b32_e32 v116, 31, v118
	v_lshl_add_u32 v112, v116, 1, v113
	v_lshrrev_b32_e32 v117, 5, v118
	v_lshl_add_u32 v112, v117, 8, v112
	v_lshl_add_u32 v113, v118, 4, v113
	v_mul_u32_u24_e32 v115, 0x6000, v116
	v_lshl_add_u32 v115, v117, 3, v115
	v_lshrrev_b32_e32 v117, 2, v118
	v_mul_u32_u24_e32 v117, 0x1c00, v117
	v_and_b32_e32 v114, 3, v118
	v_lshl_add_u32 v114, v114, 4, v117
	s_lshr_b32 s1, s0, 1
	s_lshl_b32 s1, s1, 6
	s_add_u32 s1, s1, s13
	s_and_b32 s0, s0, 1
	s_lshl_b32 s0, s0, 6
	s_and_b32 s2, s14, 0x1ff
	s_add_u32 s0, s0, s2
	s_cmp_eq_u32 s24, 9
	s_cbranch_scc1 .Levin1_gates
	s_cmp_lg_u32 s24, 0
	s_cbranch_scc1 .Levin1_noscale
	v_mul_f32_e32 v48, 0x3db504f3, v48
	v_mul_f32_e32 v49, 0x3db504f3, v49
	v_mul_f32_e32 v50, 0x3db504f3, v50
	v_mul_f32_e32 v51, 0x3db504f3, v51
	v_mul_f32_e32 v52, 0x3db504f3, v52
	v_mul_f32_e32 v53, 0x3db504f3, v53
	v_mul_f32_e32 v54, 0x3db504f3, v54
	v_mul_f32_e32 v55, 0x3db504f3, v55
	v_mul_f32_e32 v56, 0x3db504f3, v56
	v_mul_f32_e32 v57, 0x3db504f3, v57
	v_mul_f32_e32 v58, 0x3db504f3, v58
	v_mul_f32_e32 v59, 0x3db504f3, v59
	v_mul_f32_e32 v60, 0x3db504f3, v60
	v_mul_f32_e32 v61, 0x3db504f3, v61
	v_mul_f32_e32 v62, 0x3db504f3, v62
	v_mul_f32_e32 v63, 0x3db504f3, v63
	v_mul_f32_e32 v16, 0x3db504f3, v16
	v_mul_f32_e32 v17, 0x3db504f3, v17
	v_mul_f32_e32 v18, 0x3db504f3, v18
	v_mul_f32_e32 v19, 0x3db504f3, v19
	v_mul_f32_e32 v20, 0x3db504f3, v20
	v_mul_f32_e32 v21, 0x3db504f3, v21
	v_mul_f32_e32 v22, 0x3db504f3, v22
	v_mul_f32_e32 v23, 0x3db504f3, v23
	v_mul_f32_e32 v24, 0x3db504f3, v24
	v_mul_f32_e32 v25, 0x3db504f3, v25
	v_mul_f32_e32 v26, 0x3db504f3, v26
	v_mul_f32_e32 v27, 0x3db504f3, v27
	v_mul_f32_e32 v28, 0x3db504f3, v28
	v_mul_f32_e32 v29, 0x3db504f3, v29
	v_mul_f32_e32 v30, 0x3db504f3, v30
	v_mul_f32_e32 v31, 0x3db504f3, v31
	v_mul_f32_e32 v32, 0x3db504f3, v32
	v_mul_f32_e32 v33, 0x3db504f3, v33
	v_mul_f32_e32 v34, 0x3db504f3, v34
	v_mul_f32_e32 v35, 0x3db504f3, v35
	v_mul_f32_e32 v36, 0x3db504f3, v36
	v_mul_f32_e32 v37, 0x3db504f3, v37
	v_mul_f32_e32 v38, 0x3db504f3, v38
	v_mul_f32_e32 v39, 0x3db504f3, v39
	v_mul_f32_e32 v40, 0x3db504f3, v40
	v_mul_f32_e32 v41, 0x3db504f3, v41
	v_mul_f32_e32 v42, 0x3db504f3, v42
	v_mul_f32_e32 v43, 0x3db504f3, v43
	v_mul_f32_e32 v44, 0x3db504f3, v44
	v_mul_f32_e32 v45, 0x3db504f3, v45
	v_mul_f32_e32 v46, 0x3db504f3, v46
	v_mul_f32_e32 v47, 0x3db504f3, v47
	v_mul_f32_e32 v0, 0x3db504f3, v0
	v_mul_f32_e32 v1, 0x3db504f3, v1
	v_mul_f32_e32 v2, 0x3db504f3, v2
	v_mul_f32_e32 v3, 0x3db504f3, v3
	v_mul_f32_e32 v4, 0x3db504f3, v4
	v_mul_f32_e32 v5, 0x3db504f3, v5
	v_mul_f32_e32 v6, 0x3db504f3, v6
	v_mul_f32_e32 v7, 0x3db504f3, v7
	v_mul_f32_e32 v8, 0x3db504f3, v8
	v_mul_f32_e32 v9, 0x3db504f3, v9
	v_mul_f32_e32 v10, 0x3db504f3, v10
	v_mul_f32_e32 v11, 0x3db504f3, v11
	v_mul_f32_e32 v12, 0x3db504f3, v12
	v_mul_f32_e32 v13, 0x3db504f3, v13
	v_mul_f32_e32 v14, 0x3db504f3, v14
	v_mul_f32_e32 v15, 0x3db504f3, v15

.LBB0_1034:
	s_setprio 3
	v_lshl_or_b32 v115, v183, 3, v191
	v_lshrrev_b32_e32 v116, 6, v115
	v_and_b32_e32 v117, 63, v115
	v_lshlrev_b32_e32 v113, 11, v116
	v_add_u32_e32 v113, 0x10000, v113
	v_readfirstlane_b32 s100, v116
	v_and_b32_e32 v112, 31, v117
	v_lshl_add_u32 v112, v112, 1, v113
	v_lshrrev_b32_e32 v116, 5, v117
	v_lshl_add_u32 v112, v116, 8, v112
	v_lshl_add_u32 v113, v117, 4, v113
	v_lshrrev_b32_e32 v116, 2, v117
	v_mul_u32_u24_e32 v116, 0x1600, v116
	v_and_b32_e32 v114, 3, v117
	v_lshl_add_u32 v114, v114, 4, v116
	s_lshr_b32 s101, s100, 1
	s_lshl_b32 s101, s101, 6
	s_add_u32 s101, s101, s48
	s_mul_i32 s101, s101, 0x1600
	s_and_b32 s100, s100, 1
	s_lshl_b32 s100, s100, 6
	s_add_u32 s100, s100, s49
	s_add_u32 s101, s101, s100
	s_add_u32 s98, s90, 0x3971900
	s_addc_u32 s99, s91, 0
	s_add_u32 s98, s98, s101
	s_addc_u32 s99, s99, 0
	v_mul_f32_e32 v64, 0xbfb8aa3b, v48
	v_mul_f32_e32 v70, 0xbfb8aa3b, v49
	v_mul_f32_e32 v76, 0xbfb8aa3b, v50
	v_mul_f32_e32 v82, 0xbfb8aa3b, v51
	v_exp_f32_e32 v64, v64
	v_exp_f32_e32 v70, v70
	v_exp_f32_e32 v76, v76
	v_exp_f32_e32 v82, v82
	v_add_f32_e32 v64, 1.0, v64
	v_add_f32_e32 v70, 1.0, v70
	v_add_f32_e32 v76, 1.0, v76
	v_add_f32_e32 v82, 1.0, v82
	v_div_scale_f32 v65, s[2:3], v64, v64, 1.0
	v_div_scale_f32 v71, s[2:3], v70, v70, 1.0
	v_div_scale_f32 v77, s[2:3], v76, v76, 1.0
	v_div_scale_f32 v83, s[2:3], v82, v82, 1.0
	v_rcp_f32_e32 v66, v65
	v_rcp_f32_e32 v72, v71
	v_rcp_f32_e32 v78, v77
	v_rcp_f32_e32 v84, v83
	v_fma_f32 v69, -v65, v66, 1.0
	v_fma_f32 v75, -v71, v72, 1.0
	v_fma_f32 v81, -v77, v78, 1.0
	v_fma_f32 v87, -v83, v84, 1.0
	v_fmac_f32_e32 v66, v69, v66
	v_fmac_f32_e32 v72, v75, v72
	v_fmac_f32_e32 v78, v81, v78
	v_fmac_f32_e32 v84, v87, v84
	v_div_scale_f32 v67, vcc, 1.0, v64, 1.0
	v_mul_f32_e32 v88, 0xbfb8aa3b, v52
	v_mul_f32_e32 v68, v67, v66
	v_mul_f32_e32 v94, 0xbfb8aa3b, v53
	v_fma_f32 v69, -v65, v68, v67
	v_mul_f32_e32 v100, 0xbfb8aa3b, v54
	v_fmac_f32_e32 v68, v69, v66
	v_mul_f32_e32 v106, 0xbfb8aa3b, v55
	v_fma_f32 v65, -v65, v68, v67
	v_exp_f32_e32 v88, v88
	v_div_fmas_f32 v65, v65, v66, v68
	v_exp_f32_e32 v94, v94
	v_div_scale_f32 v73, vcc, 1.0, v70, 1.0
	v_exp_f32_e32 v100, v100
	v_mul_f32_e32 v74, v73, v72
	v_exp_f32_e32 v106, v106
	v_fma_f32 v75, -v71, v74, v73
	v_add_f32_e32 v88, 1.0, v88
	v_fmac_f32_e32 v74, v75, v72
	v_add_f32_e32 v94, 1.0, v94
	v_fma_f32 v71, -v71, v74, v73
	v_add_f32_e32 v100, 1.0, v100
	v_div_fmas_f32 v71, v71, v72, v74
	v_add_f32_e32 v106, 1.0, v106
	v_div_scale_f32 v79, vcc, 1.0, v76, 1.0
	v_div_scale_f32 v89, s[2:3], v88, v88, 1.0
	v_mul_f32_e32 v80, v79, v78
	v_div_scale_f32 v95, s[2:3], v94, v94, 1.0
	v_fma_f32 v81, -v77, v80, v79
	v_div_scale_f32 v101, s[2:3], v100, v100, 1.0
	v_fmac_f32_e32 v80, v81, v78
	v_div_scale_f32 v107, s[2:3], v106, v106, 1.0
	v_fma_f32 v77, -v77, v80, v79
	v_rcp_f32_e32 v90, v89
	v_div_fmas_f32 v77, v77, v78, v80
	v_rcp_f32_e32 v96, v95
	v_div_scale_f32 v85, vcc, 1.0, v82, 1.0
	v_rcp_f32_e32 v102, v101
	v_mul_f32_e32 v86, v85, v84
	v_rcp_f32_e32 v108, v107
	v_fma_f32 v87, -v83, v86, v85
	v_fma_f32 v93, -v89, v90, 1.0
	v_fmac_f32_e32 v86, v87, v84
	v_fma_f32 v99, -v95, v96, 1.0
	v_fma_f32 v83, -v83, v86, v85
	v_fma_f32 v105, -v101, v102, 1.0
	v_div_fmas_f32 v83, v83, v84, v86
	v_fma_f32 v111, -v107, v108, 1.0
	v_fmac_f32_e32 v90, v93, v90
	v_fmac_f32_e32 v96, v99, v96
	v_fmac_f32_e32 v102, v105, v102
	v_fmac_f32_e32 v108, v111, v108
	v_div_fixup_f32 v65, v65, v64, 1.0
	v_div_fixup_f32 v71, v71, v70, 1.0
	v_div_fixup_f32 v77, v77, v76, 1.0
	v_div_fixup_f32 v83, v83, v82, 1.0
	v_mul_f32_e32 v65, v48, v65
	v_mul_f32_e32 v71, v49, v71
	v_mul_f32_e32 v77, v50, v77
	v_mul_f32_e32 v83, v51, v83
	v_mul_f32_e32 v65, v32, v65
	v_mul_f32_e32 v71, v33, v71
	v_mul_f32_e32 v77, v34, v77
	v_mul_f32_e32 v83, v35, v83
	v_cvt_pk_bf16_f32 v65, v65, v65
	v_cvt_pk_bf16_f32 v71, v71, v71
	v_cvt_pk_bf16_f32 v77, v77, v77
	v_cvt_pk_bf16_f32 v83, v83, v83
	ds_write_b16 v112, v65
	ds_write_b16 v112, v71 offset:64
	ds_write_b16 v112, v77 offset:128
	ds_write_b16 v112, v83 offset:192
	v_div_scale_f32 v91, vcc, 1.0, v88, 1.0
	v_mul_f32_e32 v64, 0xbfb8aa3b, v56
	v_mul_f32_e32 v92, v91, v90
	v_mul_f32_e32 v70, 0xbfb8aa3b, v57
	v_fma_f32 v93, -v89, v92, v91
	v_mul_f32_e32 v76, 0xbfb8aa3b, v58
	v_fmac_f32_e32 v92, v93, v90
	v_mul_f32_e32 v82, 0xbfb8aa3b, v59
	v_fma_f32 v89, -v89, v92, v91
	v_exp_f32_e32 v64, v64
	v_div_fmas_f32 v89, v89, v90, v92
	v_exp_f32_e32 v70, v70
	v_div_scale_f32 v97, vcc, 1.0, v94, 1.0
	v_exp_f32_e32 v76, v76
	v_mul_f32_e32 v98, v97, v96
	v_exp_f32_e32 v82, v82
	v_fma_f32 v99, -v95, v98, v97
	v_add_f32_e32 v64, 1.0, v64
	v_fmac_f32_e32 v98, v99, v96
	v_add_f32_e32 v70, 1.0, v70
	v_fma_f32 v95, -v95, v98, v97
	v_add_f32_e32 v76, 1.0, v76
	v_div_fmas_f32 v95, v95, v96, v98
	v_add_f32_e32 v82, 1.0, v82
	v_div_scale_f32 v103, vcc, 1.0, v100, 1.0
	v_div_scale_f32 v65, s[2:3], v64, v64, 1.0
	v_mul_f32_e32 v104, v103, v102
	v_div_scale_f32 v71, s[2:3], v70, v70, 1.0
	v_fma_f32 v105, -v101, v104, v103
	v_div_scale_f32 v77, s[2:3], v76, v76, 1.0
	v_fmac_f32_e32 v104, v105, v102
	v_div_scale_f32 v83, s[2:3], v82, v82, 1.0
	v_fma_f32 v101, -v101, v104, v103
	v_rcp_f32_e32 v66, v65
	v_div_fmas_f32 v101, v101, v102, v104
	v_rcp_f32_e32 v72, v71
	v_div_scale_f32 v109, vcc, 1.0, v106, 1.0
	v_rcp_f32_e32 v78, v77
	v_mul_f32_e32 v110, v109, v108
	v_rcp_f32_e32 v84, v83
	v_fma_f32 v111, -v107, v110, v109
	v_fma_f32 v69, -v65, v66, 1.0
	v_fmac_f32_e32 v110, v111, v108
	v_fma_f32 v75, -v71, v72, 1.0
	v_fma_f32 v107, -v107, v110, v109
	v_fma_f32 v81, -v77, v78, 1.0
	v_div_fmas_f32 v107, v107, v108, v110
	v_fma_f32 v87, -v83, v84, 1.0
	v_fmac_f32_e32 v66, v69, v66
	v_fmac_f32_e32 v72, v75, v72
	v_fmac_f32_e32 v78, v81, v78
	v_fmac_f32_e32 v84, v87, v84
	v_div_fixup_f32 v89, v89, v88, 1.0
	v_div_fixup_f32 v95, v95, v94, 1.0
	v_div_fixup_f32 v101, v101, v100, 1.0
	v_div_fixup_f32 v107, v107, v106, 1.0
	v_mul_f32_e32 v89, v52, v89
	v_mul_f32_e32 v95, v53, v95
	v_mul_f32_e32 v101, v54, v101
	v_mul_f32_e32 v107, v55, v107
	v_mul_f32_e32 v89, v36, v89
	v_mul_f32_e32 v95, v37, v95
	v_mul_f32_e32 v101, v38, v101
	v_mul_f32_e32 v107, v39, v107
	v_cvt_pk_bf16_f32 v89, v89, v89
	v_cvt_pk_bf16_f32 v95, v95, v95
	v_cvt_pk_bf16_f32 v101, v101, v101
	v_cvt_pk_bf16_f32 v107, v107, v107
	ds_write_b16 v112, v89 offset:512
	ds_write_b16 v112, v95 offset:576
	ds_write_b16 v112, v101 offset:640
	ds_write_b16 v112, v107 offset:704
	v_div_scale_f32 v67, vcc, 1.0, v64, 1.0
	v_mul_f32_e32 v88, 0xbfb8aa3b, v60
	v_mul_f32_e32 v68, v67, v66
	v_mul_f32_e32 v94, 0xbfb8aa3b, v61
	v_fma_f32 v69, -v65, v68, v67
	v_mul_f32_e32 v100, 0xbfb8aa3b, v62
	v_fmac_f32_e32 v68, v69, v66
	v_mul_f32_e32 v106, 0xbfb8aa3b, v63
	v_fma_f32 v65, -v65, v68, v67
	v_exp_f32_e32 v88, v88
	v_div_fmas_f32 v65, v65, v66, v68
	v_exp_f32_e32 v94, v94
	v_div_scale_f32 v73, vcc, 1.0, v70, 1.0
	v_exp_f32_e32 v100, v100
	v_mul_f32_e32 v74, v73, v72
	v_exp_f32_e32 v106, v106
	v_fma_f32 v75, -v71, v74, v73
	v_add_f32_e32 v88, 1.0, v88
	v_fmac_f32_e32 v74, v75, v72
	v_add_f32_e32 v94, 1.0, v94
	v_fma_f32 v71, -v71, v74, v73
	v_add_f32_e32 v100, 1.0, v100
	v_div_fmas_f32 v71, v71, v72, v74
	v_add_f32_e32 v106, 1.0, v106
	v_div_scale_f32 v79, vcc, 1.0, v76, 1.0
	v_div_scale_f32 v89, s[2:3], v88, v88, 1.0
	v_mul_f32_e32 v80, v79, v78
	v_div_scale_f32 v95, s[2:3], v94, v94, 1.0
	v_fma_f32 v81, -v77, v80, v79
	v_div_scale_f32 v101, s[2:3], v100, v100, 1.0
	v_fmac_f32_e32 v80, v81, v78
	v_div_scale_f32 v107, s[2:3], v106, v106, 1.0
	v_fma_f32 v77, -v77, v80, v79
	v_rcp_f32_e32 v90, v89
	v_div_fmas_f32 v77, v77, v78, v80
	v_rcp_f32_e32 v96, v95
	v_div_scale_f32 v85, vcc, 1.0, v82, 1.0
	v_rcp_f32_e32 v102, v101
	v_mul_f32_e32 v86, v85, v84
	v_rcp_f32_e32 v108, v107
	v_fma_f32 v87, -v83, v86, v85
	v_fma_f32 v93, -v89, v90, 1.0
	v_fmac_f32_e32 v86, v87, v84
	v_fma_f32 v99, -v95, v96, 1.0
	v_fma_f32 v83, -v83, v86, v85
	v_fma_f32 v105, -v101, v102, 1.0
	v_div_fmas_f32 v83, v83, v84, v86
	v_fma_f32 v111, -v107, v108, 1.0
	v_fmac_f32_e32 v90, v93, v90
	v_fmac_f32_e32 v96, v99, v96
	v_fmac_f32_e32 v102, v105, v102
	v_fmac_f32_e32 v108, v111, v108
	v_div_fixup_f32 v65, v65, v64, 1.0
	v_div_fixup_f32 v71, v71, v70, 1.0
	v_div_fixup_f32 v77, v77, v76, 1.0
	v_div_fixup_f32 v83, v83, v82, 1.0
	v_mul_f32_e32 v65, v56, v65
	v_mul_f32_e32 v71, v57, v71
	v_mul_f32_e32 v77, v58, v77
	v_mul_f32_e32 v83, v59, v83
	v_mul_f32_e32 v65, v40, v65
	v_mul_f32_e32 v71, v41, v71
	v_mul_f32_e32 v77, v42, v77
	v_mul_f32_e32 v83, v43, v83
	v_cvt_pk_bf16_f32 v65, v65, v65
	v_cvt_pk_bf16_f32 v71, v71, v71
	v_cvt_pk_bf16_f32 v77, v77, v77
	v_cvt_pk_bf16_f32 v83, v83, v83
	ds_write_b16 v112, v65 offset:1024
	ds_write_b16 v112, v71 offset:1088
	ds_write_b16 v112, v77 offset:1152
	ds_write_b16 v112, v83 offset:1216
	v_div_scale_f32 v91, vcc, 1.0, v88, 1.0
	v_mul_f32_e32 v64, 0xbfb8aa3b, v16
	v_mul_f32_e32 v92, v91, v90
	v_mul_f32_e32 v70, 0xbfb8aa3b, v17
	v_fma_f32 v93, -v89, v92, v91
	v_mul_f32_e32 v76, 0xbfb8aa3b, v18
	v_fmac_f32_e32 v92, v93, v90
	v_mul_f32_e32 v82, 0xbfb8aa3b, v19
	v_fma_f32 v89, -v89, v92, v91
	v_exp_f32_e32 v64, v64
	v_div_fmas_f32 v89, v89, v90, v92
	v_exp_f32_e32 v70, v70
	v_div_scale_f32 v97, vcc, 1.0, v94, 1.0
	v_exp_f32_e32 v76, v76
	v_mul_f32_e32 v98, v97, v96
	v_exp_f32_e32 v82, v82
	v_fma_f32 v99, -v95, v98, v97
	v_add_f32_e32 v64, 1.0, v64
	v_fmac_f32_e32 v98, v99, v96
	v_add_f32_e32 v70, 1.0, v70
	v_fma_f32 v95, -v95, v98, v97
	v_add_f32_e32 v76, 1.0, v76
	v_div_fmas_f32 v95, v95, v96, v98
	v_add_f32_e32 v82, 1.0, v82
	v_div_scale_f32 v103, vcc, 1.0, v100, 1.0
	v_div_scale_f32 v65, s[2:3], v64, v64, 1.0
	v_mul_f32_e32 v104, v103, v102
	v_div_scale_f32 v71, s[2:3], v70, v70, 1.0
	v_fma_f32 v105, -v101, v104, v103
	v_div_scale_f32 v77, s[2:3], v76, v76, 1.0
	v_fmac_f32_e32 v104, v105, v102
	v_div_scale_f32 v83, s[2:3], v82, v82, 1.0
	v_fma_f32 v101, -v101, v104, v103
	v_rcp_f32_e32 v66, v65
	v_div_fmas_f32 v101, v101, v102, v104
	v_rcp_f32_e32 v72, v71
	v_div_scale_f32 v109, vcc, 1.0, v106, 1.0
	v_rcp_f32_e32 v78, v77
	v_mul_f32_e32 v110, v109, v108
	v_rcp_f32_e32 v84, v83
	v_fma_f32 v111, -v107, v110, v109
	v_fma_f32 v69, -v65, v66, 1.0
	v_fmac_f32_e32 v110, v111, v108
	v_fma_f32 v75, -v71, v72, 1.0
	v_fma_f32 v107, -v107, v110, v109
	v_fma_f32 v81, -v77, v78, 1.0
	v_div_fmas_f32 v107, v107, v108, v110
	v_fma_f32 v87, -v83, v84, 1.0
	v_fmac_f32_e32 v66, v69, v66
	v_fmac_f32_e32 v72, v75, v72
	v_fmac_f32_e32 v78, v81, v78
	v_fmac_f32_e32 v84, v87, v84
	v_div_fixup_f32 v89, v89, v88, 1.0
	v_div_fixup_f32 v95, v95, v94, 1.0
	v_div_fixup_f32 v101, v101, v100, 1.0
	v_div_fixup_f32 v107, v107, v106, 1.0
	v_mul_f32_e32 v89, v60, v89
	v_mul_f32_e32 v95, v61, v95
	v_mul_f32_e32 v101, v62, v101
	v_mul_f32_e32 v107, v63, v107
	v_mul_f32_e32 v89, v44, v89
	v_mul_f32_e32 v95, v45, v95
	v_mul_f32_e32 v101, v46, v101
	v_mul_f32_e32 v107, v47, v107
	v_cvt_pk_bf16_f32 v89, v89, v89
	v_cvt_pk_bf16_f32 v95, v95, v95
	v_cvt_pk_bf16_f32 v101, v101, v101
	v_cvt_pk_bf16_f32 v107, v107, v107
	ds_write_b16 v112, v89 offset:1536
	ds_write_b16 v112, v95 offset:1600
	ds_write_b16 v112, v101 offset:1664
	ds_write_b16 v112, v107 offset:1728
	ds_read_b128 v[120:123], v113
	ds_read_b128 v[124:127], v113 offset:1024
	v_div_scale_f32 v67, vcc, 1.0, v64, 1.0
	v_mul_f32_e32 v88, 0xbfb8aa3b, v20
	v_mul_f32_e32 v68, v67, v66
	v_mul_f32_e32 v94, 0xbfb8aa3b, v21
	v_fma_f32 v69, -v65, v68, v67
	v_mul_f32_e32 v100, 0xbfb8aa3b, v22
	v_fmac_f32_e32 v68, v69, v66
	v_mul_f32_e32 v106, 0xbfb8aa3b, v23
	v_fma_f32 v65, -v65, v68, v67
	v_exp_f32_e32 v88, v88
	v_div_fmas_f32 v65, v65, v66, v68
	v_exp_f32_e32 v94, v94
	v_div_scale_f32 v73, vcc, 1.0, v70, 1.0
	v_exp_f32_e32 v100, v100
	v_mul_f32_e32 v74, v73, v72
	v_exp_f32_e32 v106, v106
	v_fma_f32 v75, -v71, v74, v73
	v_add_f32_e32 v88, 1.0, v88
	v_fmac_f32_e32 v74, v75, v72
	v_add_f32_e32 v94, 1.0, v94
	v_fma_f32 v71, -v71, v74, v73
	v_add_f32_e32 v100, 1.0, v100
	v_div_fmas_f32 v71, v71, v72, v74
	v_add_f32_e32 v106, 1.0, v106
	v_div_scale_f32 v79, vcc, 1.0, v76, 1.0
	v_div_scale_f32 v89, s[2:3], v88, v88, 1.0
	v_mul_f32_e32 v80, v79, v78
	v_div_scale_f32 v95, s[2:3], v94, v94, 1.0
	v_fma_f32 v81, -v77, v80, v79
	v_div_scale_f32 v101, s[2:3], v100, v100, 1.0
	v_fmac_f32_e32 v80, v81, v78
	v_div_scale_f32 v107, s[2:3], v106, v106, 1.0
	v_fma_f32 v77, -v77, v80, v79
	v_rcp_f32_e32 v90, v89
	v_div_fmas_f32 v77, v77, v78, v80
	v_rcp_f32_e32 v96, v95
	v_div_scale_f32 v85, vcc, 1.0, v82, 1.0
	v_rcp_f32_e32 v102, v101
	v_mul_f32_e32 v86, v85, v84
	v_rcp_f32_e32 v108, v107
	v_fma_f32 v87, -v83, v86, v85
	v_fma_f32 v93, -v89, v90, 1.0
	v_fmac_f32_e32 v86, v87, v84
	v_fma_f32 v99, -v95, v96, 1.0
	v_fma_f32 v83, -v83, v86, v85
	v_fma_f32 v105, -v101, v102, 1.0
	v_div_fmas_f32 v83, v83, v84, v86
	v_fma_f32 v111, -v107, v108, 1.0
	v_fmac_f32_e32 v90, v93, v90
	v_fmac_f32_e32 v96, v99, v96
	v_fmac_f32_e32 v102, v105, v102
	v_fmac_f32_e32 v108, v111, v108
	s_waitcnt lgkmcnt(0)
	global_store_dwordx4 v114, v[120:123], s[98:99]
	s_add_u32 s98, s98, 0x16000
	s_addc_u32 s99, s99, 0
	global_store_dwordx4 v114, v[124:127], s[98:99]
	s_add_u32 s98, s98, 0x16000
	s_addc_u32 s99, s99, 0
	v_div_fixup_f32 v65, v65, v64, 1.0
	v_div_fixup_f32 v71, v71, v70, 1.0
	v_div_fixup_f32 v77, v77, v76, 1.0
	v_div_fixup_f32 v83, v83, v82, 1.0
	v_mul_f32_e32 v65, v16, v65
	v_mul_f32_e32 v71, v17, v71
	v_mul_f32_e32 v77, v18, v77
	v_mul_f32_e32 v83, v19, v83
	v_mul_f32_e32 v65, v0, v65
	v_mul_f32_e32 v71, v1, v71
	v_mul_f32_e32 v77, v2, v77
	v_mul_f32_e32 v83, v3, v83
	v_cvt_pk_bf16_f32 v65, v65, v65
	v_cvt_pk_bf16_f32 v71, v71, v71
	v_cvt_pk_bf16_f32 v77, v77, v77
	v_cvt_pk_bf16_f32 v83, v83, v83
	ds_write_b16 v112, v65
	ds_write_b16 v112, v71 offset:64
	ds_write_b16 v112, v77 offset:128
	ds_write_b16 v112, v83 offset:192
	v_div_scale_f32 v91, vcc, 1.0, v88, 1.0
	v_mul_f32_e32 v64, 0xbfb8aa3b, v24
	v_mul_f32_e32 v92, v91, v90
	v_mul_f32_e32 v70, 0xbfb8aa3b, v25
	v_fma_f32 v93, -v89, v92, v91
	v_mul_f32_e32 v76, 0xbfb8aa3b, v26
	v_fmac_f32_e32 v92, v93, v90
	v_mul_f32_e32 v82, 0xbfb8aa3b, v27
	v_fma_f32 v89, -v89, v92, v91
	v_exp_f32_e32 v64, v64
	v_div_fmas_f32 v89, v89, v90, v92
	v_exp_f32_e32 v70, v70
	v_div_scale_f32 v97, vcc, 1.0, v94, 1.0
	v_exp_f32_e32 v76, v76
	v_mul_f32_e32 v98, v97, v96
	v_exp_f32_e32 v82, v82
	v_fma_f32 v99, -v95, v98, v97
	v_add_f32_e32 v64, 1.0, v64
	v_fmac_f32_e32 v98, v99, v96
	v_add_f32_e32 v70, 1.0, v70
	v_fma_f32 v95, -v95, v98, v97
	v_add_f32_e32 v76, 1.0, v76
	v_div_fmas_f32 v95, v95, v96, v98
	v_add_f32_e32 v82, 1.0, v82
	v_div_scale_f32 v103, vcc, 1.0, v100, 1.0
	v_div_scale_f32 v65, s[2:3], v64, v64, 1.0
	v_mul_f32_e32 v104, v103, v102
	v_div_scale_f32 v71, s[2:3], v70, v70, 1.0
	v_fma_f32 v105, -v101, v104, v103
	v_div_scale_f32 v77, s[2:3], v76, v76, 1.0
	v_fmac_f32_e32 v104, v105, v102
	v_div_scale_f32 v83, s[2:3], v82, v82, 1.0
	v_fma_f32 v101, -v101, v104, v103
	v_rcp_f32_e32 v66, v65
	v_div_fmas_f32 v101, v101, v102, v104
	v_rcp_f32_e32 v72, v71
	v_div_scale_f32 v109, vcc, 1.0, v106, 1.0
	v_rcp_f32_e32 v78, v77
	v_mul_f32_e32 v110, v109, v108
	v_rcp_f32_e32 v84, v83
	v_fma_f32 v111, -v107, v110, v109
	v_fma_f32 v69, -v65, v66, 1.0
	v_fmac_f32_e32 v110, v111, v108
	v_fma_f32 v75, -v71, v72, 1.0
	v_fma_f32 v107, -v107, v110, v109
	v_fma_f32 v81, -v77, v78, 1.0
	v_div_fmas_f32 v107, v107, v108, v110
	v_fma_f32 v87, -v83, v84, 1.0
	v_fmac_f32_e32 v66, v69, v66
	v_fmac_f32_e32 v72, v75, v72
	v_fmac_f32_e32 v78, v81, v78
	v_fmac_f32_e32 v84, v87, v84
	v_div_fixup_f32 v89, v89, v88, 1.0
	v_div_fixup_f32 v95, v95, v94, 1.0
	v_div_fixup_f32 v101, v101, v100, 1.0
	v_div_fixup_f32 v107, v107, v106, 1.0
	v_mul_f32_e32 v89, v20, v89
	v_mul_f32_e32 v95, v21, v95
	v_mul_f32_e32 v101, v22, v101
	v_mul_f32_e32 v107, v23, v107
	v_mul_f32_e32 v89, v4, v89
	v_mul_f32_e32 v95, v5, v95
	v_mul_f32_e32 v101, v6, v101
	v_mul_f32_e32 v107, v7, v107
	v_cvt_pk_bf16_f32 v89, v89, v89
	v_cvt_pk_bf16_f32 v95, v95, v95
	v_cvt_pk_bf16_f32 v101, v101, v101
	v_cvt_pk_bf16_f32 v107, v107, v107
	ds_write_b16 v112, v89 offset:512
	ds_write_b16 v112, v95 offset:576
	ds_write_b16 v112, v101 offset:640
	ds_write_b16 v112, v107 offset:704
	v_div_scale_f32 v67, vcc, 1.0, v64, 1.0
	v_mul_f32_e32 v88, 0xbfb8aa3b, v28
	v_mul_f32_e32 v68, v67, v66
	v_mul_f32_e32 v94, 0xbfb8aa3b, v29
	v_fma_f32 v69, -v65, v68, v67
	v_mul_f32_e32 v100, 0xbfb8aa3b, v30
	v_fmac_f32_e32 v68, v69, v66
	v_mul_f32_e32 v106, 0xbfb8aa3b, v31
	v_fma_f32 v65, -v65, v68, v67
	v_exp_f32_e32 v88, v88
	v_div_fmas_f32 v65, v65, v66, v68
	v_exp_f32_e32 v94, v94
	v_div_scale_f32 v73, vcc, 1.0, v70, 1.0
	v_exp_f32_e32 v100, v100
	v_mul_f32_e32 v74, v73, v72
	v_exp_f32_e32 v106, v106
	v_fma_f32 v75, -v71, v74, v73
	v_add_f32_e32 v88, 1.0, v88
	v_fmac_f32_e32 v74, v75, v72
	v_add_f32_e32 v94, 1.0, v94
	v_fma_f32 v71, -v71, v74, v73
	v_add_f32_e32 v100, 1.0, v100
	v_div_fmas_f32 v71, v71, v72, v74
	v_add_f32_e32 v106, 1.0, v106
	v_div_scale_f32 v79, vcc, 1.0, v76, 1.0
	v_div_scale_f32 v89, s[2:3], v88, v88, 1.0
	v_mul_f32_e32 v80, v79, v78
	v_div_scale_f32 v95, s[2:3], v94, v94, 1.0
	v_fma_f32 v81, -v77, v80, v79
	v_div_scale_f32 v101, s[2:3], v100, v100, 1.0
	v_fmac_f32_e32 v80, v81, v78
	v_div_scale_f32 v107, s[2:3], v106, v106, 1.0
	v_fma_f32 v77, -v77, v80, v79
	v_rcp_f32_e32 v90, v89
	v_div_fmas_f32 v77, v77, v78, v80
	v_rcp_f32_e32 v96, v95
	v_div_scale_f32 v85, vcc, 1.0, v82, 1.0
	v_rcp_f32_e32 v102, v101
	v_mul_f32_e32 v86, v85, v84
	v_rcp_f32_e32 v108, v107
	v_fma_f32 v87, -v83, v86, v85
	v_fma_f32 v93, -v89, v90, 1.0
	v_fmac_f32_e32 v86, v87, v84
	v_fma_f32 v99, -v95, v96, 1.0
	v_fma_f32 v83, -v83, v86, v85
	v_fma_f32 v105, -v101, v102, 1.0
	v_div_fmas_f32 v83, v83, v84, v86
	v_fma_f32 v111, -v107, v108, 1.0
	v_fmac_f32_e32 v90, v93, v90
	v_fmac_f32_e32 v96, v99, v96
	v_fmac_f32_e32 v102, v105, v102
	v_fmac_f32_e32 v108, v111, v108
	v_div_fixup_f32 v65, v65, v64, 1.0
	v_div_fixup_f32 v71, v71, v70, 1.0
	v_div_fixup_f32 v77, v77, v76, 1.0
	v_div_fixup_f32 v83, v83, v82, 1.0
	v_mul_f32_e32 v65, v24, v65
	v_mul_f32_e32 v71, v25, v71
	v_mul_f32_e32 v77, v26, v77
	v_mul_f32_e32 v83, v27, v83
	v_mul_f32_e32 v65, v8, v65
	v_mul_f32_e32 v71, v9, v71
	v_mul_f32_e32 v77, v10, v77
	v_mul_f32_e32 v83, v11, v83
	v_cvt_pk_bf16_f32 v65, v65, v65
	v_cvt_pk_bf16_f32 v71, v71, v71
	v_cvt_pk_bf16_f32 v77, v77, v77
	v_cvt_pk_bf16_f32 v83, v83, v83
	ds_write_b16 v112, v65 offset:1024
	ds_write_b16 v112, v71 offset:1088
	ds_write_b16 v112, v77 offset:1152
	ds_write_b16 v112, v83 offset:1216
	v_div_scale_f32 v91, vcc, 1.0, v88, 1.0
	v_mul_f32_e32 v92, v91, v90
	v_fma_f32 v93, -v89, v92, v91
	v_fmac_f32_e32 v92, v93, v90
	v_fma_f32 v89, -v89, v92, v91
	v_div_fmas_f32 v89, v89, v90, v92
	v_div_scale_f32 v97, vcc, 1.0, v94, 1.0
	v_mul_f32_e32 v98, v97, v96
	v_fma_f32 v99, -v95, v98, v97
	v_fmac_f32_e32 v98, v99, v96
	v_fma_f32 v95, -v95, v98, v97
	v_div_fmas_f32 v95, v95, v96, v98
	v_div_scale_f32 v103, vcc, 1.0, v100, 1.0
	v_mul_f32_e32 v104, v103, v102
	v_fma_f32 v105, -v101, v104, v103
	v_fmac_f32_e32 v104, v105, v102
	v_fma_f32 v101, -v101, v104, v103
	v_div_fmas_f32 v101, v101, v102, v104
	v_div_scale_f32 v109, vcc, 1.0, v106, 1.0
	v_mul_f32_e32 v110, v109, v108
	v_fma_f32 v111, -v107, v110, v109
	v_fmac_f32_e32 v110, v111, v108
	v_fma_f32 v107, -v107, v110, v109
	v_div_fmas_f32 v107, v107, v108, v110
	v_div_fixup_f32 v89, v89, v88, 1.0
	v_div_fixup_f32 v95, v95, v94, 1.0
	v_div_fixup_f32 v101, v101, v100, 1.0
	v_div_fixup_f32 v107, v107, v106, 1.0
	v_mul_f32_e32 v89, v28, v89
	v_mul_f32_e32 v95, v29, v95
	v_mul_f32_e32 v101, v30, v101
	v_mul_f32_e32 v107, v31, v107
	v_mul_f32_e32 v89, v12, v89
	v_mul_f32_e32 v95, v13, v95
	v_mul_f32_e32 v101, v14, v101
	v_mul_f32_e32 v107, v15, v107
	v_cvt_pk_bf16_f32 v89, v89, v89
	v_cvt_pk_bf16_f32 v95, v95, v95
	v_cvt_pk_bf16_f32 v101, v101, v101
	v_cvt_pk_bf16_f32 v107, v107, v107
	ds_write_b16 v112, v89 offset:1536
	ds_write_b16 v112, v95 offset:1600
	ds_write_b16 v112, v101 offset:1664
	ds_write_b16 v112, v107 offset:1728
	ds_read_b128 v[120:123], v113
	ds_read_b128 v[124:127], v113 offset:1024
	s_waitcnt lgkmcnt(0)
	global_store_dwordx4 v114, v[120:123], s[98:99]
	s_add_u32 s98, s98, 0x16000
	s_addc_u32 s99, s99, 0
	global_store_dwordx4 v114, v[124:127], s[98:99]
	s_add_u32 s98, s98, 0x16000
	s_addc_u32 s99, s99, 0
	s_add_i32 s57, s57, s92
	s_cmpk_gt_i32 s57, 0x107f
	s_cbranch_scc1 .LBB0_1043
.LBB0_1035:
	s_and_b32 s2, s57, 7
	s_bfe_u32 s3, s57, 0x60003
	s_lshr_b32 s6, s57, 9
	s_lshl_b32 s6, s6, 6
	s_add_u32 s3, s3, s6
	s_mul_hi_u32 s6, s3, 0xaaaaaaab
	s_lshr_b32 s6, s6, 3
	s_mul_i32 s7, s6, 12
	s_sub_u32 s3, s3, s7
	s_mul_i32 s2, s2, 12
	s_add_u32 s2, s2, s3
	s_lshl_b32 s48, s2, 7
	s_lshl_b32 s49, s6, 7
	s_setprio 0
	v_lshl_or_b32 v64, v183, 3, v191
	v_and_b32_e32 v65, 63, v64
	v_lshrrev_b32_e32 v66, 3, v65
	v_lshrrev_b32_e32 v67, 4, v65
	v_xor_b32_e32 v67, v67, v65
	v_and_b32_e32 v67, 7, v67
	v_lshlrev_b32_e32 v67, 4, v67
	s_movk_i32 s99, 0x800
	v_mad_u32_u24 v112, v66, s99, v67
	v_xor_b32_e32 v68, 64, v112
	v_add_u32_e32 v113, 0x3c00, v68
	v_add_u32_e32 v114, 0x7800, v112
	v_add_u32_e32 v115, 0xb400, v68
	v_add_u32_e32 v116, 0x10000, v112
	v_add_u32_e32 v117, 0x13c00, v68
	v_add_u32_e32 v118, 0x17800, v112
	v_add_u32_e32 v119, 0x1b400, v68
	v_and_b32_e32 v69, 31, v64
	v_bfe_u32 v70, v64, 5, 1
	v_bfe_u32 v71, v64, 1, 3
	v_xor_b32_e32 v71, v71, v70
	v_lshlrev_b32_e32 v71, 4, v71
	v_bfe_u32 v72, v64, 7, 1
	v_lshl_or_b32 v72, v72, 6, v69
	v_lshl_add_u32 v120, v72, 7, v71
	v_bfe_u32 v73, v64, 6, 1
	v_lshl_or_b32 v73, v73, 6, v69
	v_lshl_add_u32 v124, v73, 7, v71
	v_add_u32_e32 v124, 0x4000, v124
	v_xor_b32_e32 v121, 32, v120
	v_xor_b32_e32 v125, 32, v124
	v_xor_b32_e32 v122, 64, v120
	v_xor_b32_e32 v126, 64, v124
	v_xor_b32_e32 v123, 96, v120
	v_xor_b32_e32 v127, 96, v124
	v_lshrrev_b32_e32 v74, 6, v64
	s_nop 0
	v_readfirstlane_b32 s100, v74
	s_nop 3
	s_lshl_b32 s98, s100, 13
	s_mov_b32 s101, 0xb40000
	s_mov_b32 s99, s49
	s_cmp_lt_u32 s100, 2
	s_cmov_b32 s101, 0xb171900
	s_cmov_b32 s99, s48
	s_and_b32 s100, s100, 1
	s_lshl_b32 s100, s100, 6
	s_add_u32 s99, s99, s100
	s_mul_i32 s99, s99, 0x800
	s_add_u32 s99, s99, s101
	s_add_u32 s2, s90, s99
	s_addc_u32 s3, s91, 0
	v_readlane_b32 s99, v251, 0
	s_cmp_lg_u32 s99, 0
	s_cbranch_scc1 .Lg2_pref
	s_add_u32 m0, s98, 0x0
	s_nop 0
	global_load_lds_dwordx4 v112, s[2:3] offset:0
	global_load_lds_dwordx4 v113, s[2:3] offset:1024
	global_load_lds_dwordx4 v114, s[2:3] offset:2048
	global_load_lds_dwordx4 v115, s[2:3] offset:3072
	s_add_u32 m0, s98, 0x1000
	s_nop 0
	global_load_lds_dwordx4 v116, s[2:3] offset:0
	global_load_lds_dwordx4 v117, s[2:3] offset:1024
	global_load_lds_dwordx4 v118, s[2:3] offset:2048
	global_load_lds_dwordx4 v119, s[2:3] offset:3072
	s_add_u32 s2, s2, 0x80
	s_addc_u32 s3, s3, 0
	s_add_u32 m0, s98, 0x8000
	s_nop 0
	global_load_lds_dwordx4 v112, s[2:3] offset:0
	global_load_lds_dwordx4 v113, s[2:3] offset:1024
	global_load_lds_dwordx4 v114, s[2:3] offset:2048
	global_load_lds_dwordx4 v115, s[2:3] offset:3072
	s_add_u32 m0, s98, 0x9000
	s_nop 0
	global_load_lds_dwordx4 v116, s[2:3] offset:0
	global_load_lds_dwordx4 v117, s[2:3] offset:1024
	global_load_lds_dwordx4 v118, s[2:3] offset:2048
	global_load_lds_dwordx4 v119, s[2:3] offset:3072
	s_add_u32 s2, s2, 0x80
	s_addc_u32 s3, s3, 0
	s_mov_b32 s101, 0
	s_branch .Lg2_prol

.LBB0_1099:
	s_cmp_ge_i32 s65, s72
	s_cselect_b64 s[36:37], -1, 0
	s_sub_i32 s2, s65, s72
	s_and_b32 s3, 1, s2
	s_lshr_b32 s2, s2, 1
	s_add_i32 s2, s2, s72
	s_cmp_eq_u32 s3, 1
	s_cselect_b32 s3, 0x580, 0
	s_cmp_lt_i32 s65, s72
	s_cselect_b32 s2, s65, s2
	s_mul_hi_i32 s6, s2, 0x2aaaaaab
	s_cselect_b32 s8, 44, 22
	s_cselect_b32 s3, 0, s3
	s_lshr_b32 s7, s6, 31
	s_ashr_i32 s6, s6, 4
	s_add_i32 s6, s6, s7
	s_mul_i32 s7, s6, 0x60
	s_sub_i32 s2, s2, s7
	s_lshl_b32 s9, s2, 7
	s_lshl_b32 s24, s3, 1
	s_lshl_b32 s10, s6, 7
	s_setprio 0
	v_lshl_or_b32 v64, v183, 3, v191
	v_and_b32_e32 v65, 63, v64
	v_lshrrev_b32_e32 v66, 3, v65
	v_lshrrev_b32_e32 v67, 4, v65
	v_xor_b32_e32 v67, v67, v65
	v_and_b32_e32 v67, 7, v67
	v_lshlrev_b32_e32 v67, 4, v67
	s_movk_i32 s99, 0x1600
	v_mad_u32_u24 v112, v66, s99, v67
	v_xor_b32_e32 v68, 64, v112
	v_add_u32_e32 v113, 0xac00, v68
	v_add_u32_e32 v114, 0x15800, v112
	v_add_u32_e32 v115, 0x20400, v68
	v_add_u32_e32 v116, 0x2c000, v112
	v_add_u32_e32 v117, 0x36c00, v68
	v_add_u32_e32 v118, 0x41800, v112
	v_add_u32_e32 v119, 0x4c400, v68
	v_and_b32_e32 v69, 31, v64
	v_bfe_u32 v70, v64, 5, 1
	v_bfe_u32 v71, v64, 1, 3
	v_xor_b32_e32 v71, v71, v70
	v_lshlrev_b32_e32 v71, 4, v71
	v_bfe_u32 v72, v64, 7, 1
	v_lshl_or_b32 v72, v72, 6, v69
	v_lshl_add_u32 v120, v72, 7, v71
	v_bfe_u32 v73, v64, 6, 1
	v_lshl_or_b32 v73, v73, 6, v69
	v_lshl_add_u32 v124, v73, 7, v71
	v_add_u32_e32 v124, 0x4000, v124
	v_xor_b32_e32 v121, 32, v120
	v_xor_b32_e32 v125, 32, v124
	v_xor_b32_e32 v122, 64, v120
	v_xor_b32_e32 v126, 64, v124
	v_xor_b32_e32 v123, 96, v120
	v_xor_b32_e32 v127, 96, v124
	v_lshrrev_b32_e32 v74, 6, v64
	s_nop 0
	v_readfirstlane_b32 s100, v74
	s_nop 3
	s_lshl_b32 s98, s100, 13
	s_mov_b32 s101, 0x2140000
	s_mov_b32 s99, s10
	s_cmp_lt_u32 s100, 2
	s_cmov_b32 s101, 0x3971900
	s_cmov_b32 s99, s9
	s_and_b32 s100, s100, 1
	s_lshl_b32 s100, s100, 6
	s_add_u32 s99, s99, s100
	s_mul_i32 s99, s99, 0x1600
	s_add_u32 s99, s99, s101
	s_add_u32 s99, s99, s24
	s_add_u32 s2, s90, s99
	s_addc_u32 s3, s91, 0
	s_add_u32 m0, s98, 0x0
	s_nop 0
	global_load_lds_dwordx4 v112, s[2:3] offset:0
	global_load_lds_dwordx4 v113, s[2:3] offset:1024
	global_load_lds_dwordx4 v114, s[2:3] offset:2048
	global_load_lds_dwordx4 v115, s[2:3] offset:3072
	s_add_u32 m0, s98, 0x1000
	s_nop 0
	global_load_lds_dwordx4 v116, s[2:3] offset:0
	global_load_lds_dwordx4 v117, s[2:3] offset:1024
	global_load_lds_dwordx4 v118, s[2:3] offset:2048
	global_load_lds_dwordx4 v119, s[2:3] offset:3072
	s_add_u32 s2, s2, 0x80
	s_addc_u32 s3, s3, 0
	s_add_u32 m0, s98, 0x8000
	s_nop 0
	global_load_lds_dwordx4 v112, s[2:3] offset:0
	global_load_lds_dwordx4 v113, s[2:3] offset:1024
	global_load_lds_dwordx4 v114, s[2:3] offset:2048
	global_load_lds_dwordx4 v115, s[2:3] offset:3072
	s_add_u32 m0, s98, 0x9000
	s_nop 0
	global_load_lds_dwordx4 v116, s[2:3] offset:0
	global_load_lds_dwordx4 v117, s[2:3] offset:1024
	global_load_lds_dwordx4 v118, s[2:3] offset:2048
	global_load_lds_dwordx4 v119, s[2:3] offset:3072
	s_add_u32 s2, s2, 0x80
	s_addc_u32 s3, s3, 0
	v_mov_b32_e32 v48, 0
	v_mov_b32_e32 v49, 0
	v_mov_b32_e32 v50, 0
	v_mov_b32_e32 v51, 0
	v_mov_b32_e32 v52, 0
	v_mov_b32_e32 v53, 0
	v_mov_b32_e32 v54, 0
	v_mov_b32_e32 v55, 0
	v_mov_b32_e32 v56, 0
	v_mov_b32_e32 v57, 0
	v_mov_b32_e32 v58, 0
	v_mov_b32_e32 v59, 0
	v_mov_b32_e32 v60, 0
	v_mov_b32_e32 v61, 0
	v_mov_b32_e32 v62, 0
	v_mov_b32_e32 v63, 0
	v_mov_b32_e32 v16, 0
	v_mov_b32_e32 v17, 0
	v_mov_b32_e32 v18, 0
	v_mov_b32_e32 v19, 0
	v_mov_b32_e32 v20, 0
	v_mov_b32_e32 v21, 0
	v_mov_b32_e32 v22, 0
	v_mov_b32_e32 v23, 0
	v_mov_b32_e32 v24, 0
	v_mov_b32_e32 v25, 0
	v_mov_b32_e32 v26, 0
	v_mov_b32_e32 v27, 0
	v_mov_b32_e32 v28, 0
	v_mov_b32_e32 v29, 0
	v_mov_b32_e32 v30, 0
	v_mov_b32_e32 v31, 0
	v_mov_b32_e32 v32, 0
	v_mov_b32_e32 v33, 0
	v_mov_b32_e32 v34, 0
	v_mov_b32_e32 v35, 0
	v_mov_b32_e32 v36, 0
	v_mov_b32_e32 v37, 0
	v_mov_b32_e32 v38, 0
	v_mov_b32_e32 v39, 0
	v_mov_b32_e32 v40, 0
	v_mov_b32_e32 v41, 0
	v_mov_b32_e32 v42, 0
	v_mov_b32_e32 v43, 0
	v_mov_b32_e32 v44, 0
	v_mov_b32_e32 v45, 0
	v_mov_b32_e32 v46, 0
	v_mov_b32_e32 v47, 0
	v_mov_b32_e32 v0, 0
	v_mov_b32_e32 v1, 0
	v_mov_b32_e32 v2, 0
	v_mov_b32_e32 v3, 0
	v_mov_b32_e32 v4, 0
	v_mov_b32_e32 v5, 0
	v_mov_b32_e32 v6, 0
	v_mov_b32_e32 v7, 0
	v_mov_b32_e32 v8, 0
	v_mov_b32_e32 v9, 0
	v_mov_b32_e32 v10, 0
	v_mov_b32_e32 v11, 0
	v_mov_b32_e32 v12, 0
	v_mov_b32_e32 v13, 0
	v_mov_b32_e32 v14, 0
	v_mov_b32_e32 v15, 0
	s_lshr_b32 s7, s8, 1
	s_sub_u32 s7, s7, 1
	s_waitcnt vmcnt(8)

.LBB0_1510:
	s_mul_hi_i32 s6, s74, 0x2aaaaaab
	s_lshr_b32 s7, s6, 31
	s_ashr_i32 s6, s6, 4
	s_add_i32 s6, s6, s7
	s_mul_i32 s7, s6, 0x60
	s_sub_i32 s7, s74, s7
	s_lshl_b32 s11, s7, 7
	s_lshl_b32 s10, s6, 7
	s_setprio 0
	v_lshl_or_b32 v64, v183, 3, v191
	v_and_b32_e32 v65, 63, v64
	v_lshrrev_b32_e32 v66, 3, v65
	v_lshrrev_b32_e32 v67, 4, v65
	v_xor_b32_e32 v67, v67, v65
	v_and_b32_e32 v67, 7, v67
	v_lshlrev_b32_e32 v67, 4, v67
	s_movk_i32 s99, 0x800
	v_mad_u32_u24 v112, v66, s99, v67
	v_xor_b32_e32 v68, 64, v112
	v_add_u32_e32 v113, 0x3c00, v68
	v_add_u32_e32 v114, 0x7800, v112
	v_add_u32_e32 v115, 0xb400, v68
	v_add_u32_e32 v116, 0x10000, v112
	v_add_u32_e32 v117, 0x13c00, v68
	v_add_u32_e32 v118, 0x17800, v112
	v_add_u32_e32 v119, 0x1b400, v68
	v_and_b32_e32 v69, 31, v64
	v_bfe_u32 v70, v64, 5, 1
	v_bfe_u32 v71, v64, 1, 3
	v_xor_b32_e32 v71, v71, v70
	v_lshlrev_b32_e32 v71, 4, v71
	v_bfe_u32 v72, v64, 7, 1
	v_lshl_or_b32 v72, v72, 6, v69
	v_lshl_add_u32 v120, v72, 7, v71
	v_bfe_u32 v73, v64, 6, 1
	v_lshl_or_b32 v73, v73, 6, v69
	v_lshl_add_u32 v124, v73, 7, v71
	v_add_u32_e32 v124, 0x4000, v124
	v_xor_b32_e32 v121, 32, v120
	v_xor_b32_e32 v125, 32, v124
	v_xor_b32_e32 v122, 64, v120
	v_xor_b32_e32 v126, 64, v124
	v_xor_b32_e32 v123, 96, v120
	v_xor_b32_e32 v127, 96, v124
	v_lshrrev_b32_e32 v74, 6, v64
	s_nop 0
	v_readfirstlane_b32 s100, v74
	s_nop 3
	s_lshl_b32 s98, s100, 13
	s_mov_b32 s101, 0x2c40000
	s_mov_b32 s99, s10
	s_cmp_lt_u32 s100, 2
	s_cmov_b32 s101, 0xb171900
	s_cmov_b32 s99, s11
	s_and_b32 s100, s100, 1
	s_lshl_b32 s100, s100, 6
	s_add_u32 s99, s99, s100
	s_mul_i32 s99, s99, 0x800
	s_add_u32 s99, s99, s101
	s_add_u32 s6, s90, s99
	s_addc_u32 s7, s91, 0
	s_add_u32 m0, s98, 0x0
	s_nop 0
	global_load_lds_dwordx4 v112, s[6:7] offset:0
	global_load_lds_dwordx4 v113, s[6:7] offset:1024
	global_load_lds_dwordx4 v114, s[6:7] offset:2048
	global_load_lds_dwordx4 v115, s[6:7] offset:3072
	s_add_u32 m0, s98, 0x1000
	s_nop 0
	global_load_lds_dwordx4 v116, s[6:7] offset:0
	global_load_lds_dwordx4 v117, s[6:7] offset:1024
	global_load_lds_dwordx4 v118, s[6:7] offset:2048
	global_load_lds_dwordx4 v119, s[6:7] offset:3072
	s_add_u32 s6, s6, 0x80
	s_addc_u32 s7, s7, 0
	s_add_u32 m0, s98, 0x8000
	s_nop 0
	global_load_lds_dwordx4 v112, s[6:7] offset:0
	global_load_lds_dwordx4 v113, s[6:7] offset:1024
	global_load_lds_dwordx4 v114, s[6:7] offset:2048
	global_load_lds_dwordx4 v115, s[6:7] offset:3072
	s_add_u32 m0, s98, 0x9000
	s_nop 0
	global_load_lds_dwordx4 v116, s[6:7] offset:0
	global_load_lds_dwordx4 v117, s[6:7] offset:1024
	global_load_lds_dwordx4 v118, s[6:7] offset:2048
	global_load_lds_dwordx4 v119, s[6:7] offset:3072
	s_add_u32 s6, s6, 0x80
	s_addc_u32 s7, s7, 0
	v_mov_b32_e32 v48, 0
	v_mov_b32_e32 v49, 0
	v_mov_b32_e32 v50, 0
	v_mov_b32_e32 v51, 0
	v_mov_b32_e32 v52, 0
	v_mov_b32_e32 v53, 0
	v_mov_b32_e32 v54, 0
	v_mov_b32_e32 v55, 0
	v_mov_b32_e32 v56, 0
	v_mov_b32_e32 v57, 0
	v_mov_b32_e32 v58, 0
	v_mov_b32_e32 v59, 0
	v_mov_b32_e32 v60, 0
	v_mov_b32_e32 v61, 0
	v_mov_b32_e32 v62, 0
	v_mov_b32_e32 v63, 0
	v_mov_b32_e32 v16, 0
	v_mov_b32_e32 v17, 0
	v_mov_b32_e32 v18, 0
	v_mov_b32_e32 v19, 0
	v_mov_b32_e32 v20, 0
	v_mov_b32_e32 v21, 0
	v_mov_b32_e32 v22, 0
	v_mov_b32_e32 v23, 0
	v_mov_b32_e32 v24, 0
	v_mov_b32_e32 v25, 0
	v_mov_b32_e32 v26, 0
	v_mov_b32_e32 v27, 0
	v_mov_b32_e32 v28, 0
	v_mov_b32_e32 v29, 0
	v_mov_b32_e32 v30, 0
	v_mov_b32_e32 v31, 0
	v_mov_b32_e32 v32, 0
	v_mov_b32_e32 v33, 0
	v_mov_b32_e32 v34, 0
	v_mov_b32_e32 v35, 0
	v_mov_b32_e32 v36, 0
	v_mov_b32_e32 v37, 0
	v_mov_b32_e32 v38, 0
	v_mov_b32_e32 v39, 0
	v_mov_b32_e32 v40, 0
	v_mov_b32_e32 v41, 0
	v_mov_b32_e32 v42, 0
	v_mov_b32_e32 v43, 0
	v_mov_b32_e32 v44, 0
	v_mov_b32_e32 v45, 0
	v_mov_b32_e32 v46, 0
	v_mov_b32_e32 v47, 0
	v_mov_b32_e32 v0, 0
	v_mov_b32_e32 v1, 0
	v_mov_b32_e32 v2, 0
	v_mov_b32_e32 v3, 0
	v_mov_b32_e32 v4, 0
	v_mov_b32_e32 v5, 0
	v_mov_b32_e32 v6, 0
	v_mov_b32_e32 v7, 0
	v_mov_b32_e32 v8, 0
	v_mov_b32_e32 v9, 0
	v_mov_b32_e32 v10, 0
	v_mov_b32_e32 v11, 0
	v_mov_b32_e32 v12, 0
	v_mov_b32_e32 v13, 0
	v_mov_b32_e32 v14, 0
	v_mov_b32_e32 v15, 0
	s_movk_i32 s8, 7
	s_waitcnt vmcnt(8)

.LBB0_1518:
	s_setprio 3
	s_lshr_b32 s12, s10, 10
	s_cmp_gt_u32 s12, 1
	s_cbranch_scc1 .Lodin4_old
	v_lshl_or_b32 v116, v183, 3, v191
	v_lshrrev_b32_e32 v117, 6, v116
	v_and_b32_e32 v118, 63, v116
	v_lshlrev_b32_e32 v113, 11, v117
	v_add_u32_e32 v113, 0x10000, v113
	v_readfirstlane_b32 s6, v117
	v_and_b32_e32 v116, 31, v118
	v_lshl_add_u32 v112, v116, 1, v113
	v_lshrrev_b32_e32 v117, 5, v118
	v_lshl_add_u32 v112, v117, 8, v112
	v_lshl_add_u32 v113, v118, 4, v113
	v_lshlrev_b32_e32 v115, 2, v116
	v_lshl_add_u32 v115, v117, 14, v115
	v_lshrrev_b32_e32 v117, 2, v118
	v_and_b32_e32 v114, 3, v118
	v_lshlrev_b32_e32 v114, 4, v114
	v_lshl_add_u32 v114, v117, 11, v114
	s_lshr_b32 s7, s6, 1
	s_lshl_b32 s7, s7, 6
	s_add_u32 s7, s7, s11
	s_and_b32 s6, s6, 1
	s_lshl_b32 s6, s6, 6
	s_and_b32 s8, s10, 0x3ff
	s_add_u32 s6, s6, s8
	s_cmp_eq_u32 s12, 2
	s_cbranch_scc1 .Lodin4_vseg
	s_cmp_ge_u32 s11, 0x2000
	s_cbranch_scc1 .Lodin4_rope

.LBB0_1874:
	s_cmp_ge_i32 s55, s72
	s_cselect_b64 s[36:37], -1, 0
	s_sub_i32 s4, s55, s72
	s_and_b32 s5, 1, s4
	s_lshr_b32 s4, s4, 1
	s_add_i32 s4, s4, s72
	s_cmp_eq_u32 s5, 1
	s_cselect_b32 s5, 0x200, 0
	s_cmp_lt_i32 s55, s72
	s_cselect_b32 s4, s55, s4
	s_mul_hi_i32 s6, s4, 0x2aaaaaab
	s_cselect_b32 s8, 16, 8
	s_cselect_b32 s5, 0, s5
	s_lshr_b32 s7, s6, 31
	s_ashr_i32 s6, s6, 4
	s_add_i32 s6, s6, s7
	s_mul_i32 s7, s6, 0x60
	s_sub_i32 s4, s4, s7
	s_lshl_b32 s9, s4, 7
	s_lshl_b32 s10, s6, 7
	s_lshl_b32 s26, s5, 1
	s_setprio 0
	v_lshl_or_b32 v64, v183, 3, v191
	v_and_b32_e32 v65, 63, v64
	v_lshrrev_b32_e32 v66, 3, v65
	v_lshrrev_b32_e32 v67, 4, v65
	v_xor_b32_e32 v67, v67, v65
	v_and_b32_e32 v67, 7, v67
	v_lshlrev_b32_e32 v67, 4, v67
	s_movk_i32 s99, 0x800
	v_mad_u32_u24 v112, v66, s99, v67
	v_xor_b32_e32 v68, 64, v112
	v_add_u32_e32 v113, 0x3c00, v68
	v_add_u32_e32 v114, 0x7800, v112
	v_add_u32_e32 v115, 0xb400, v68
	v_add_u32_e32 v116, 0x10000, v112
	v_add_u32_e32 v117, 0x13c00, v68
	v_add_u32_e32 v118, 0x17800, v112
	v_add_u32_e32 v119, 0x1b400, v68
	v_and_b32_e32 v69, 31, v64
	v_bfe_u32 v70, v64, 5, 1
	v_bfe_u32 v71, v64, 1, 3
	v_xor_b32_e32 v71, v71, v70
	v_lshlrev_b32_e32 v71, 4, v71
	v_bfe_u32 v72, v64, 7, 1
	v_lshl_or_b32 v72, v72, 6, v69
	v_lshl_add_u32 v120, v72, 7, v71
	v_bfe_u32 v73, v64, 6, 1
	v_lshl_or_b32 v73, v73, 6, v69
	v_lshl_add_u32 v124, v73, 7, v71
	v_add_u32_e32 v124, 0x4000, v124
	v_xor_b32_e32 v121, 32, v120
	v_xor_b32_e32 v125, 32, v124
	v_xor_b32_e32 v122, 64, v120
	v_xor_b32_e32 v126, 64, v124
	v_xor_b32_e32 v123, 96, v120
	v_xor_b32_e32 v127, 96, v124
	v_lshrrev_b32_e32 v74, 6, v64
	s_nop 0
	v_readfirstlane_b32 s100, v74
	s_nop 3
	s_lshl_b32 s98, s100, 13
	s_mov_b32 s101, 0x3240000
	s_mov_b32 s99, s10
	s_cmp_lt_u32 s100, 2
	s_cmov_b32 s101, 0xc971900
	s_cmov_b32 s99, s9
	s_and_b32 s100, s100, 1
	s_lshl_b32 s100, s100, 6
	s_add_u32 s99, s99, s100
	s_mul_i32 s99, s99, 0x800
	s_add_u32 s99, s99, s101
	s_add_u32 s99, s99, s26
	s_add_u32 s4, s90, s99
	s_addc_u32 s5, s91, 0
	s_add_u32 m0, s98, 0x0
	s_nop 0
	global_load_lds_dwordx4 v112, s[4:5] offset:0
	global_load_lds_dwordx4 v113, s[4:5] offset:1024
	global_load_lds_dwordx4 v114, s[4:5] offset:2048
	global_load_lds_dwordx4 v115, s[4:5] offset:3072
	s_add_u32 m0, s98, 0x1000
	s_nop 0
	global_load_lds_dwordx4 v116, s[4:5] offset:0
	global_load_lds_dwordx4 v117, s[4:5] offset:1024
	global_load_lds_dwordx4 v118, s[4:5] offset:2048
	global_load_lds_dwordx4 v119, s[4:5] offset:3072
	s_add_u32 s4, s4, 0x80
	s_addc_u32 s5, s5, 0
	s_add_u32 m0, s98, 0x8000
	s_nop 0
	global_load_lds_dwordx4 v112, s[4:5] offset:0
	global_load_lds_dwordx4 v113, s[4:5] offset:1024
	global_load_lds_dwordx4 v114, s[4:5] offset:2048
	global_load_lds_dwordx4 v115, s[4:5] offset:3072
	s_add_u32 m0, s98, 0x9000
	s_nop 0
	global_load_lds_dwordx4 v116, s[4:5] offset:0
	global_load_lds_dwordx4 v117, s[4:5] offset:1024
	global_load_lds_dwordx4 v118, s[4:5] offset:2048
	global_load_lds_dwordx4 v119, s[4:5] offset:3072
	s_add_u32 s4, s4, 0x80
	s_addc_u32 s5, s5, 0
	v_mov_b32_e32 v48, 0
	v_mov_b32_e32 v49, 0
	v_mov_b32_e32 v50, 0
	v_mov_b32_e32 v51, 0
	v_mov_b32_e32 v52, 0
	v_mov_b32_e32 v53, 0
	v_mov_b32_e32 v54, 0
	v_mov_b32_e32 v55, 0
	v_mov_b32_e32 v56, 0
	v_mov_b32_e32 v57, 0
	v_mov_b32_e32 v58, 0
	v_mov_b32_e32 v59, 0
	v_mov_b32_e32 v60, 0
	v_mov_b32_e32 v61, 0
	v_mov_b32_e32 v62, 0
	v_mov_b32_e32 v63, 0
	v_mov_b32_e32 v16, 0
	v_mov_b32_e32 v17, 0
	v_mov_b32_e32 v18, 0
	v_mov_b32_e32 v19, 0
	v_mov_b32_e32 v20, 0
	v_mov_b32_e32 v21, 0
	v_mov_b32_e32 v22, 0
	v_mov_b32_e32 v23, 0
	v_mov_b32_e32 v24, 0
	v_mov_b32_e32 v25, 0
	v_mov_b32_e32 v26, 0
	v_mov_b32_e32 v27, 0
	v_mov_b32_e32 v28, 0
	v_mov_b32_e32 v29, 0
	v_mov_b32_e32 v30, 0
	v_mov_b32_e32 v31, 0
	v_mov_b32_e32 v32, 0
	v_mov_b32_e32 v33, 0
	v_mov_b32_e32 v34, 0
	v_mov_b32_e32 v35, 0
	v_mov_b32_e32 v36, 0
	v_mov_b32_e32 v37, 0
	v_mov_b32_e32 v38, 0
	v_mov_b32_e32 v39, 0
	v_mov_b32_e32 v40, 0
	v_mov_b32_e32 v41, 0
	v_mov_b32_e32 v42, 0
	v_mov_b32_e32 v43, 0
	v_mov_b32_e32 v44, 0
	v_mov_b32_e32 v45, 0
	v_mov_b32_e32 v46, 0
	v_mov_b32_e32 v47, 0
	v_mov_b32_e32 v0, 0
	v_mov_b32_e32 v1, 0
	v_mov_b32_e32 v2, 0
	v_mov_b32_e32 v3, 0
	v_mov_b32_e32 v4, 0
	v_mov_b32_e32 v5, 0
	v_mov_b32_e32 v6, 0
	v_mov_b32_e32 v7, 0
	v_mov_b32_e32 v8, 0
	v_mov_b32_e32 v9, 0
	v_mov_b32_e32 v10, 0
	v_mov_b32_e32 v11, 0
	v_mov_b32_e32 v12, 0
	v_mov_b32_e32 v13, 0
	v_mov_b32_e32 v14, 0
	v_mov_b32_e32 v15, 0
	s_lshr_b32 s7, s8, 1
	s_sub_u32 s7, s7, 1
	s_waitcnt vmcnt(8)

.LBB0_2283:
	s_setprio 3
	v_lshl_or_b32 v115, v183, 3, v191
	v_lshrrev_b32_e32 v116, 6, v115
	v_and_b32_e32 v117, 63, v115
	v_lshlrev_b32_e32 v113, 11, v116
	v_add_u32_e32 v113, 0x10000, v113
	v_readfirstlane_b32 s100, v116
	v_and_b32_e32 v112, 31, v117
	v_lshl_add_u32 v112, v112, 1, v113
	v_lshrrev_b32_e32 v116, 5, v117
	v_lshl_add_u32 v112, v116, 8, v112
	v_lshl_add_u32 v113, v117, 4, v113
	v_lshrrev_b32_e32 v116, 2, v117
	v_mul_u32_u24_e32 v116, 0x1600, v116
	v_and_b32_e32 v114, 3, v117
	v_lshl_add_u32 v114, v114, 4, v116
	s_lshr_b32 s101, s100, 1
	s_lshl_b32 s101, s101, 6
	s_add_u32 s101, s101, s48
	s_mul_i32 s101, s101, 0x1600
	s_and_b32 s100, s100, 1
	s_lshl_b32 s100, s100, 6
	s_add_u32 s100, s100, s49
	s_add_u32 s101, s101, s100
	s_add_u32 s98, s90, 0x3971900
	s_addc_u32 s99, s91, 0
	s_add_u32 s98, s98, s101
	s_addc_u32 s99, s99, 0
	v_mul_f32_e32 v64, 0xbfb8aa3b, v48
	v_mul_f32_e32 v70, 0xbfb8aa3b, v49
	v_mul_f32_e32 v76, 0xbfb8aa3b, v50
	v_mul_f32_e32 v82, 0xbfb8aa3b, v51
	v_exp_f32_e32 v64, v64
	v_exp_f32_e32 v70, v70
	v_exp_f32_e32 v76, v76
	v_exp_f32_e32 v82, v82
	v_add_f32_e32 v64, 1.0, v64
	v_add_f32_e32 v70, 1.0, v70
	v_add_f32_e32 v76, 1.0, v76
	v_add_f32_e32 v82, 1.0, v82
	v_div_scale_f32 v65, s[4:5], v64, v64, 1.0
	v_div_scale_f32 v71, s[4:5], v70, v70, 1.0
	v_div_scale_f32 v77, s[4:5], v76, v76, 1.0
	v_div_scale_f32 v83, s[4:5], v82, v82, 1.0
	v_rcp_f32_e32 v66, v65
	v_rcp_f32_e32 v72, v71
	v_rcp_f32_e32 v78, v77
	v_rcp_f32_e32 v84, v83
	v_fma_f32 v69, -v65, v66, 1.0
	v_fma_f32 v75, -v71, v72, 1.0
	v_fma_f32 v81, -v77, v78, 1.0
	v_fma_f32 v87, -v83, v84, 1.0
	v_fmac_f32_e32 v66, v69, v66
	v_fmac_f32_e32 v72, v75, v72
	v_fmac_f32_e32 v78, v81, v78
	v_fmac_f32_e32 v84, v87, v84
	v_div_scale_f32 v67, vcc, 1.0, v64, 1.0
	v_mul_f32_e32 v88, 0xbfb8aa3b, v52
	v_mul_f32_e32 v68, v67, v66
	v_mul_f32_e32 v94, 0xbfb8aa3b, v53
	v_fma_f32 v69, -v65, v68, v67
	v_mul_f32_e32 v100, 0xbfb8aa3b, v54
	v_fmac_f32_e32 v68, v69, v66
	v_mul_f32_e32 v106, 0xbfb8aa3b, v55
	v_fma_f32 v65, -v65, v68, v67
	v_exp_f32_e32 v88, v88
	v_div_fmas_f32 v65, v65, v66, v68
	v_exp_f32_e32 v94, v94
	v_div_scale_f32 v73, vcc, 1.0, v70, 1.0
	v_exp_f32_e32 v100, v100
	v_mul_f32_e32 v74, v73, v72
	v_exp_f32_e32 v106, v106
	v_fma_f32 v75, -v71, v74, v73
	v_add_f32_e32 v88, 1.0, v88
	v_fmac_f32_e32 v74, v75, v72
	v_add_f32_e32 v94, 1.0, v94
	v_fma_f32 v71, -v71, v74, v73
	v_add_f32_e32 v100, 1.0, v100
	v_div_fmas_f32 v71, v71, v72, v74
	v_add_f32_e32 v106, 1.0, v106
	v_div_scale_f32 v79, vcc, 1.0, v76, 1.0
	v_div_scale_f32 v89, s[4:5], v88, v88, 1.0
	v_mul_f32_e32 v80, v79, v78
	v_div_scale_f32 v95, s[4:5], v94, v94, 1.0
	v_fma_f32 v81, -v77, v80, v79
	v_div_scale_f32 v101, s[4:5], v100, v100, 1.0
	v_fmac_f32_e32 v80, v81, v78
	v_div_scale_f32 v107, s[4:5], v106, v106, 1.0
	v_fma_f32 v77, -v77, v80, v79
	v_rcp_f32_e32 v90, v89
	v_div_fmas_f32 v77, v77, v78, v80
	v_rcp_f32_e32 v96, v95
	v_div_scale_f32 v85, vcc, 1.0, v82, 1.0
	v_rcp_f32_e32 v102, v101
	v_mul_f32_e32 v86, v85, v84
	v_rcp_f32_e32 v108, v107
	v_fma_f32 v87, -v83, v86, v85
	v_fma_f32 v93, -v89, v90, 1.0
	v_fmac_f32_e32 v86, v87, v84
	v_fma_f32 v99, -v95, v96, 1.0
	v_fma_f32 v83, -v83, v86, v85
	v_fma_f32 v105, -v101, v102, 1.0
	v_div_fmas_f32 v83, v83, v84, v86
	v_fma_f32 v111, -v107, v108, 1.0
	v_fmac_f32_e32 v90, v93, v90
	v_fmac_f32_e32 v96, v99, v96
	v_fmac_f32_e32 v102, v105, v102
	v_fmac_f32_e32 v108, v111, v108
	v_div_fixup_f32 v65, v65, v64, 1.0
	v_div_fixup_f32 v71, v71, v70, 1.0
	v_div_fixup_f32 v77, v77, v76, 1.0
	v_div_fixup_f32 v83, v83, v82, 1.0
	v_mul_f32_e32 v65, v48, v65
	v_mul_f32_e32 v71, v49, v71
	v_mul_f32_e32 v77, v50, v77
	v_mul_f32_e32 v83, v51, v83
	v_mul_f32_e32 v65, v32, v65
	v_mul_f32_e32 v71, v33, v71
	v_mul_f32_e32 v77, v34, v77
	v_mul_f32_e32 v83, v35, v83
	v_cvt_pk_bf16_f32 v65, v65, v65
	v_cvt_pk_bf16_f32 v71, v71, v71
	v_cvt_pk_bf16_f32 v77, v77, v77
	v_cvt_pk_bf16_f32 v83, v83, v83
	ds_write_b16 v112, v65
	ds_write_b16 v112, v71 offset:64
	ds_write_b16 v112, v77 offset:128
	ds_write_b16 v112, v83 offset:192
	v_div_scale_f32 v91, vcc, 1.0, v88, 1.0
	v_mul_f32_e32 v64, 0xbfb8aa3b, v56
	v_mul_f32_e32 v92, v91, v90
	v_mul_f32_e32 v70, 0xbfb8aa3b, v57
	v_fma_f32 v93, -v89, v92, v91
	v_mul_f32_e32 v76, 0xbfb8aa3b, v58
	v_fmac_f32_e32 v92, v93, v90
	v_mul_f32_e32 v82, 0xbfb8aa3b, v59
	v_fma_f32 v89, -v89, v92, v91
	v_exp_f32_e32 v64, v64
	v_div_fmas_f32 v89, v89, v90, v92
	v_exp_f32_e32 v70, v70
	v_div_scale_f32 v97, vcc, 1.0, v94, 1.0
	v_exp_f32_e32 v76, v76
	v_mul_f32_e32 v98, v97, v96
	v_exp_f32_e32 v82, v82
	v_fma_f32 v99, -v95, v98, v97
	v_add_f32_e32 v64, 1.0, v64
	v_fmac_f32_e32 v98, v99, v96
	v_add_f32_e32 v70, 1.0, v70
	v_fma_f32 v95, -v95, v98, v97
	v_add_f32_e32 v76, 1.0, v76
	v_div_fmas_f32 v95, v95, v96, v98
	v_add_f32_e32 v82, 1.0, v82
	v_div_scale_f32 v103, vcc, 1.0, v100, 1.0
	v_div_scale_f32 v65, s[4:5], v64, v64, 1.0
	v_mul_f32_e32 v104, v103, v102
	v_div_scale_f32 v71, s[4:5], v70, v70, 1.0
	v_fma_f32 v105, -v101, v104, v103
	v_div_scale_f32 v77, s[4:5], v76, v76, 1.0
	v_fmac_f32_e32 v104, v105, v102
	v_div_scale_f32 v83, s[4:5], v82, v82, 1.0
	v_fma_f32 v101, -v101, v104, v103
	v_rcp_f32_e32 v66, v65
	v_div_fmas_f32 v101, v101, v102, v104
	v_rcp_f32_e32 v72, v71
	v_div_scale_f32 v109, vcc, 1.0, v106, 1.0
	v_rcp_f32_e32 v78, v77
	v_mul_f32_e32 v110, v109, v108
	v_rcp_f32_e32 v84, v83
	v_fma_f32 v111, -v107, v110, v109
	v_fma_f32 v69, -v65, v66, 1.0
	v_fmac_f32_e32 v110, v111, v108
	v_fma_f32 v75, -v71, v72, 1.0
	v_fma_f32 v107, -v107, v110, v109
	v_fma_f32 v81, -v77, v78, 1.0
	v_div_fmas_f32 v107, v107, v108, v110
	v_fma_f32 v87, -v83, v84, 1.0
	v_fmac_f32_e32 v66, v69, v66
	v_fmac_f32_e32 v72, v75, v72
	v_fmac_f32_e32 v78, v81, v78
	v_fmac_f32_e32 v84, v87, v84
	v_div_fixup_f32 v89, v89, v88, 1.0
	v_div_fixup_f32 v95, v95, v94, 1.0
	v_div_fixup_f32 v101, v101, v100, 1.0
	v_div_fixup_f32 v107, v107, v106, 1.0
	v_mul_f32_e32 v89, v52, v89
	v_mul_f32_e32 v95, v53, v95
	v_mul_f32_e32 v101, v54, v101
	v_mul_f32_e32 v107, v55, v107
	v_mul_f32_e32 v89, v36, v89
	v_mul_f32_e32 v95, v37, v95
	v_mul_f32_e32 v101, v38, v101
	v_mul_f32_e32 v107, v39, v107
	v_cvt_pk_bf16_f32 v89, v89, v89
	v_cvt_pk_bf16_f32 v95, v95, v95
	v_cvt_pk_bf16_f32 v101, v101, v101
	v_cvt_pk_bf16_f32 v107, v107, v107
	ds_write_b16 v112, v89 offset:512
	ds_write_b16 v112, v95 offset:576
	ds_write_b16 v112, v101 offset:640
	ds_write_b16 v112, v107 offset:704
	v_div_scale_f32 v67, vcc, 1.0, v64, 1.0
	v_mul_f32_e32 v88, 0xbfb8aa3b, v60
	v_mul_f32_e32 v68, v67, v66
	v_mul_f32_e32 v94, 0xbfb8aa3b, v61
	v_fma_f32 v69, -v65, v68, v67
	v_mul_f32_e32 v100, 0xbfb8aa3b, v62
	v_fmac_f32_e32 v68, v69, v66
	v_mul_f32_e32 v106, 0xbfb8aa3b, v63
	v_fma_f32 v65, -v65, v68, v67
	v_exp_f32_e32 v88, v88
	v_div_fmas_f32 v65, v65, v66, v68
	v_exp_f32_e32 v94, v94
	v_div_scale_f32 v73, vcc, 1.0, v70, 1.0
	v_exp_f32_e32 v100, v100
	v_mul_f32_e32 v74, v73, v72
	v_exp_f32_e32 v106, v106
	v_fma_f32 v75, -v71, v74, v73
	v_add_f32_e32 v88, 1.0, v88
	v_fmac_f32_e32 v74, v75, v72
	v_add_f32_e32 v94, 1.0, v94
	v_fma_f32 v71, -v71, v74, v73
	v_add_f32_e32 v100, 1.0, v100
	v_div_fmas_f32 v71, v71, v72, v74
	v_add_f32_e32 v106, 1.0, v106
	v_div_scale_f32 v79, vcc, 1.0, v76, 1.0
	v_div_scale_f32 v89, s[4:5], v88, v88, 1.0
	v_mul_f32_e32 v80, v79, v78
	v_div_scale_f32 v95, s[4:5], v94, v94, 1.0
	v_fma_f32 v81, -v77, v80, v79
	v_div_scale_f32 v101, s[4:5], v100, v100, 1.0
	v_fmac_f32_e32 v80, v81, v78
	v_div_scale_f32 v107, s[4:5], v106, v106, 1.0
	v_fma_f32 v77, -v77, v80, v79
	v_rcp_f32_e32 v90, v89
	v_div_fmas_f32 v77, v77, v78, v80
	v_rcp_f32_e32 v96, v95
	v_div_scale_f32 v85, vcc, 1.0, v82, 1.0
	v_rcp_f32_e32 v102, v101
	v_mul_f32_e32 v86, v85, v84
	v_rcp_f32_e32 v108, v107
	v_fma_f32 v87, -v83, v86, v85
	v_fma_f32 v93, -v89, v90, 1.0
	v_fmac_f32_e32 v86, v87, v84
	v_fma_f32 v99, -v95, v96, 1.0
	v_fma_f32 v83, -v83, v86, v85
	v_fma_f32 v105, -v101, v102, 1.0
	v_div_fmas_f32 v83, v83, v84, v86
	v_fma_f32 v111, -v107, v108, 1.0
	v_fmac_f32_e32 v90, v93, v90
	v_fmac_f32_e32 v96, v99, v96
	v_fmac_f32_e32 v102, v105, v102
	v_fmac_f32_e32 v108, v111, v108
	v_div_fixup_f32 v65, v65, v64, 1.0
	v_div_fixup_f32 v71, v71, v70, 1.0
	v_div_fixup_f32 v77, v77, v76, 1.0
	v_div_fixup_f32 v83, v83, v82, 1.0
	v_mul_f32_e32 v65, v56, v65
	v_mul_f32_e32 v71, v57, v71
	v_mul_f32_e32 v77, v58, v77
	v_mul_f32_e32 v83, v59, v83
	v_mul_f32_e32 v65, v40, v65
	v_mul_f32_e32 v71, v41, v71
	v_mul_f32_e32 v77, v42, v77
	v_mul_f32_e32 v83, v43, v83
	v_cvt_pk_bf16_f32 v65, v65, v65
	v_cvt_pk_bf16_f32 v71, v71, v71
	v_cvt_pk_bf16_f32 v77, v77, v77
	v_cvt_pk_bf16_f32 v83, v83, v83
	ds_write_b16 v112, v65 offset:1024
	ds_write_b16 v112, v71 offset:1088
	ds_write_b16 v112, v77 offset:1152
	ds_write_b16 v112, v83 offset:1216
	v_div_scale_f32 v91, vcc, 1.0, v88, 1.0
	v_mul_f32_e32 v64, 0xbfb8aa3b, v16
	v_mul_f32_e32 v92, v91, v90
	v_mul_f32_e32 v70, 0xbfb8aa3b, v17
	v_fma_f32 v93, -v89, v92, v91
	v_mul_f32_e32 v76, 0xbfb8aa3b, v18
	v_fmac_f32_e32 v92, v93, v90
	v_mul_f32_e32 v82, 0xbfb8aa3b, v19
	v_fma_f32 v89, -v89, v92, v91
	v_exp_f32_e32 v64, v64
	v_div_fmas_f32 v89, v89, v90, v92
	v_exp_f32_e32 v70, v70
	v_div_scale_f32 v97, vcc, 1.0, v94, 1.0
	v_exp_f32_e32 v76, v76
	v_mul_f32_e32 v98, v97, v96
	v_exp_f32_e32 v82, v82
	v_fma_f32 v99, -v95, v98, v97
	v_add_f32_e32 v64, 1.0, v64
	v_fmac_f32_e32 v98, v99, v96
	v_add_f32_e32 v70, 1.0, v70
	v_fma_f32 v95, -v95, v98, v97
	v_add_f32_e32 v76, 1.0, v76
	v_div_fmas_f32 v95, v95, v96, v98
	v_add_f32_e32 v82, 1.0, v82
	v_div_scale_f32 v103, vcc, 1.0, v100, 1.0
	v_div_scale_f32 v65, s[4:5], v64, v64, 1.0
	v_mul_f32_e32 v104, v103, v102
	v_div_scale_f32 v71, s[4:5], v70, v70, 1.0
	v_fma_f32 v105, -v101, v104, v103
	v_div_scale_f32 v77, s[4:5], v76, v76, 1.0
	v_fmac_f32_e32 v104, v105, v102
	v_div_scale_f32 v83, s[4:5], v82, v82, 1.0
	v_fma_f32 v101, -v101, v104, v103
	v_rcp_f32_e32 v66, v65
	v_div_fmas_f32 v101, v101, v102, v104
	v_rcp_f32_e32 v72, v71
	v_div_scale_f32 v109, vcc, 1.0, v106, 1.0
	v_rcp_f32_e32 v78, v77
	v_mul_f32_e32 v110, v109, v108
	v_rcp_f32_e32 v84, v83
	v_fma_f32 v111, -v107, v110, v109
	v_fma_f32 v69, -v65, v66, 1.0
	v_fmac_f32_e32 v110, v111, v108
	v_fma_f32 v75, -v71, v72, 1.0
	v_fma_f32 v107, -v107, v110, v109
	v_fma_f32 v81, -v77, v78, 1.0
	v_div_fmas_f32 v107, v107, v108, v110
	v_fma_f32 v87, -v83, v84, 1.0
	v_fmac_f32_e32 v66, v69, v66
	v_fmac_f32_e32 v72, v75, v72
	v_fmac_f32_e32 v78, v81, v78
	v_fmac_f32_e32 v84, v87, v84
	v_div_fixup_f32 v89, v89, v88, 1.0
	v_div_fixup_f32 v95, v95, v94, 1.0
	v_div_fixup_f32 v101, v101, v100, 1.0
	v_div_fixup_f32 v107, v107, v106, 1.0
	v_mul_f32_e32 v89, v60, v89
	v_mul_f32_e32 v95, v61, v95
	v_mul_f32_e32 v101, v62, v101
	v_mul_f32_e32 v107, v63, v107
	v_mul_f32_e32 v89, v44, v89
	v_mul_f32_e32 v95, v45, v95
	v_mul_f32_e32 v101, v46, v101
	v_mul_f32_e32 v107, v47, v107
	v_cvt_pk_bf16_f32 v89, v89, v89
	v_cvt_pk_bf16_f32 v95, v95, v95
	v_cvt_pk_bf16_f32 v101, v101, v101
	v_cvt_pk_bf16_f32 v107, v107, v107
	ds_write_b16 v112, v89 offset:1536
	ds_write_b16 v112, v95 offset:1600
	ds_write_b16 v112, v101 offset:1664
	ds_write_b16 v112, v107 offset:1728
	ds_read_b128 v[120:123], v113
	ds_read_b128 v[124:127], v113 offset:1024
	v_div_scale_f32 v67, vcc, 1.0, v64, 1.0
	v_mul_f32_e32 v88, 0xbfb8aa3b, v20
	v_mul_f32_e32 v68, v67, v66
	v_mul_f32_e32 v94, 0xbfb8aa3b, v21
	v_fma_f32 v69, -v65, v68, v67
	v_mul_f32_e32 v100, 0xbfb8aa3b, v22
	v_fmac_f32_e32 v68, v69, v66
	v_mul_f32_e32 v106, 0xbfb8aa3b, v23
	v_fma_f32 v65, -v65, v68, v67
	v_exp_f32_e32 v88, v88
	v_div_fmas_f32 v65, v65, v66, v68
	v_exp_f32_e32 v94, v94
	v_div_scale_f32 v73, vcc, 1.0, v70, 1.0
	v_exp_f32_e32 v100, v100
	v_mul_f32_e32 v74, v73, v72
	v_exp_f32_e32 v106, v106
	v_fma_f32 v75, -v71, v74, v73
	v_add_f32_e32 v88, 1.0, v88
	v_fmac_f32_e32 v74, v75, v72
	v_add_f32_e32 v94, 1.0, v94
	v_fma_f32 v71, -v71, v74, v73
	v_add_f32_e32 v100, 1.0, v100
	v_div_fmas_f32 v71, v71, v72, v74
	v_add_f32_e32 v106, 1.0, v106
	v_div_scale_f32 v79, vcc, 1.0, v76, 1.0
	v_div_scale_f32 v89, s[4:5], v88, v88, 1.0
	v_mul_f32_e32 v80, v79, v78
	v_div_scale_f32 v95, s[4:5], v94, v94, 1.0
	v_fma_f32 v81, -v77, v80, v79
	v_div_scale_f32 v101, s[4:5], v100, v100, 1.0
	v_fmac_f32_e32 v80, v81, v78
	v_div_scale_f32 v107, s[4:5], v106, v106, 1.0
	v_fma_f32 v77, -v77, v80, v79
	v_rcp_f32_e32 v90, v89
	v_div_fmas_f32 v77, v77, v78, v80
	v_rcp_f32_e32 v96, v95
	v_div_scale_f32 v85, vcc, 1.0, v82, 1.0
	v_rcp_f32_e32 v102, v101
	v_mul_f32_e32 v86, v85, v84
	v_rcp_f32_e32 v108, v107
	v_fma_f32 v87, -v83, v86, v85
	v_fma_f32 v93, -v89, v90, 1.0
	v_fmac_f32_e32 v86, v87, v84
	v_fma_f32 v99, -v95, v96, 1.0
	v_fma_f32 v83, -v83, v86, v85
	v_fma_f32 v105, -v101, v102, 1.0
	v_div_fmas_f32 v83, v83, v84, v86
	v_fma_f32 v111, -v107, v108, 1.0
	v_fmac_f32_e32 v90, v93, v90
	v_fmac_f32_e32 v96, v99, v96
	v_fmac_f32_e32 v102, v105, v102
	v_fmac_f32_e32 v108, v111, v108
	s_waitcnt lgkmcnt(0)
	global_store_dwordx4 v114, v[120:123], s[98:99]
	s_add_u32 s98, s98, 0x16000
	s_addc_u32 s99, s99, 0
	global_store_dwordx4 v114, v[124:127], s[98:99]
	s_add_u32 s98, s98, 0x16000
	s_addc_u32 s99, s99, 0
	v_div_fixup_f32 v65, v65, v64, 1.0
	v_div_fixup_f32 v71, v71, v70, 1.0
	v_div_fixup_f32 v77, v77, v76, 1.0
	v_div_fixup_f32 v83, v83, v82, 1.0
	v_mul_f32_e32 v65, v16, v65
	v_mul_f32_e32 v71, v17, v71
	v_mul_f32_e32 v77, v18, v77
	v_mul_f32_e32 v83, v19, v83
	v_mul_f32_e32 v65, v0, v65
	v_mul_f32_e32 v71, v1, v71
	v_mul_f32_e32 v77, v2, v77
	v_mul_f32_e32 v83, v3, v83
	v_cvt_pk_bf16_f32 v65, v65, v65
	v_cvt_pk_bf16_f32 v71, v71, v71
	v_cvt_pk_bf16_f32 v77, v77, v77
	v_cvt_pk_bf16_f32 v83, v83, v83
	ds_write_b16 v112, v65
	ds_write_b16 v112, v71 offset:64
	ds_write_b16 v112, v77 offset:128
	ds_write_b16 v112, v83 offset:192
	v_div_scale_f32 v91, vcc, 1.0, v88, 1.0
	v_mul_f32_e32 v64, 0xbfb8aa3b, v24
	v_mul_f32_e32 v92, v91, v90
	v_mul_f32_e32 v70, 0xbfb8aa3b, v25
	v_fma_f32 v93, -v89, v92, v91
	v_mul_f32_e32 v76, 0xbfb8aa3b, v26
	v_fmac_f32_e32 v92, v93, v90
	v_mul_f32_e32 v82, 0xbfb8aa3b, v27
	v_fma_f32 v89, -v89, v92, v91
	v_exp_f32_e32 v64, v64
	v_div_fmas_f32 v89, v89, v90, v92
	v_exp_f32_e32 v70, v70
	v_div_scale_f32 v97, vcc, 1.0, v94, 1.0
	v_exp_f32_e32 v76, v76
	v_mul_f32_e32 v98, v97, v96
	v_exp_f32_e32 v82, v82
	v_fma_f32 v99, -v95, v98, v97
	v_add_f32_e32 v64, 1.0, v64
	v_fmac_f32_e32 v98, v99, v96
	v_add_f32_e32 v70, 1.0, v70
	v_fma_f32 v95, -v95, v98, v97
	v_add_f32_e32 v76, 1.0, v76
	v_div_fmas_f32 v95, v95, v96, v98
	v_add_f32_e32 v82, 1.0, v82
	v_div_scale_f32 v103, vcc, 1.0, v100, 1.0
	v_div_scale_f32 v65, s[4:5], v64, v64, 1.0
	v_mul_f32_e32 v104, v103, v102
	v_div_scale_f32 v71, s[4:5], v70, v70, 1.0
	v_fma_f32 v105, -v101, v104, v103
	v_div_scale_f32 v77, s[4:5], v76, v76, 1.0
	v_fmac_f32_e32 v104, v105, v102
	v_div_scale_f32 v83, s[4:5], v82, v82, 1.0
	v_fma_f32 v101, -v101, v104, v103
	v_rcp_f32_e32 v66, v65
	v_div_fmas_f32 v101, v101, v102, v104
	v_rcp_f32_e32 v72, v71
	v_div_scale_f32 v109, vcc, 1.0, v106, 1.0
	v_rcp_f32_e32 v78, v77
	v_mul_f32_e32 v110, v109, v108
	v_rcp_f32_e32 v84, v83
	v_fma_f32 v111, -v107, v110, v109
	v_fma_f32 v69, -v65, v66, 1.0
	v_fmac_f32_e32 v110, v111, v108
	v_fma_f32 v75, -v71, v72, 1.0
	v_fma_f32 v107, -v107, v110, v109
	v_fma_f32 v81, -v77, v78, 1.0
	v_div_fmas_f32 v107, v107, v108, v110
	v_fma_f32 v87, -v83, v84, 1.0
	v_fmac_f32_e32 v66, v69, v66
	v_fmac_f32_e32 v72, v75, v72
	v_fmac_f32_e32 v78, v81, v78
	v_fmac_f32_e32 v84, v87, v84
	v_div_fixup_f32 v89, v89, v88, 1.0
	v_div_fixup_f32 v95, v95, v94, 1.0
	v_div_fixup_f32 v101, v101, v100, 1.0
	v_div_fixup_f32 v107, v107, v106, 1.0
	v_mul_f32_e32 v89, v20, v89
	v_mul_f32_e32 v95, v21, v95
	v_mul_f32_e32 v101, v22, v101
	v_mul_f32_e32 v107, v23, v107
	v_mul_f32_e32 v89, v4, v89
	v_mul_f32_e32 v95, v5, v95
	v_mul_f32_e32 v101, v6, v101
	v_mul_f32_e32 v107, v7, v107
	v_cvt_pk_bf16_f32 v89, v89, v89
	v_cvt_pk_bf16_f32 v95, v95, v95
	v_cvt_pk_bf16_f32 v101, v101, v101
	v_cvt_pk_bf16_f32 v107, v107, v107
	ds_write_b16 v112, v89 offset:512
	ds_write_b16 v112, v95 offset:576
	ds_write_b16 v112, v101 offset:640
	ds_write_b16 v112, v107 offset:704
	v_div_scale_f32 v67, vcc, 1.0, v64, 1.0
	v_mul_f32_e32 v88, 0xbfb8aa3b, v28
	v_mul_f32_e32 v68, v67, v66
	v_mul_f32_e32 v94, 0xbfb8aa3b, v29
	v_fma_f32 v69, -v65, v68, v67
	v_mul_f32_e32 v100, 0xbfb8aa3b, v30
	v_fmac_f32_e32 v68, v69, v66
	v_mul_f32_e32 v106, 0xbfb8aa3b, v31
	v_fma_f32 v65, -v65, v68, v67
	v_exp_f32_e32 v88, v88
	v_div_fmas_f32 v65, v65, v66, v68
	v_exp_f32_e32 v94, v94
	v_div_scale_f32 v73, vcc, 1.0, v70, 1.0
	v_exp_f32_e32 v100, v100
	v_mul_f32_e32 v74, v73, v72
	v_exp_f32_e32 v106, v106
	v_fma_f32 v75, -v71, v74, v73
	v_add_f32_e32 v88, 1.0, v88
	v_fmac_f32_e32 v74, v75, v72
	v_add_f32_e32 v94, 1.0, v94
	v_fma_f32 v71, -v71, v74, v73
	v_add_f32_e32 v100, 1.0, v100
	v_div_fmas_f32 v71, v71, v72, v74
	v_add_f32_e32 v106, 1.0, v106
	v_div_scale_f32 v79, vcc, 1.0, v76, 1.0
	v_div_scale_f32 v89, s[4:5], v88, v88, 1.0
	v_mul_f32_e32 v80, v79, v78
	v_div_scale_f32 v95, s[4:5], v94, v94, 1.0
	v_fma_f32 v81, -v77, v80, v79
	v_div_scale_f32 v101, s[4:5], v100, v100, 1.0
	v_fmac_f32_e32 v80, v81, v78
	v_div_scale_f32 v107, s[4:5], v106, v106, 1.0
	v_fma_f32 v77, -v77, v80, v79
	v_rcp_f32_e32 v90, v89
	v_div_fmas_f32 v77, v77, v78, v80
	v_rcp_f32_e32 v96, v95
	v_div_scale_f32 v85, vcc, 1.0, v82, 1.0
	v_rcp_f32_e32 v102, v101
	v_mul_f32_e32 v86, v85, v84
	v_rcp_f32_e32 v108, v107
	v_fma_f32 v87, -v83, v86, v85
	v_fma_f32 v93, -v89, v90, 1.0
	v_fmac_f32_e32 v86, v87, v84
	v_fma_f32 v99, -v95, v96, 1.0
	v_fma_f32 v83, -v83, v86, v85
	v_fma_f32 v105, -v101, v102, 1.0
	v_div_fmas_f32 v83, v83, v84, v86
	v_fma_f32 v111, -v107, v108, 1.0
	v_fmac_f32_e32 v90, v93, v90
	v_fmac_f32_e32 v96, v99, v96
	v_fmac_f32_e32 v102, v105, v102
	v_fmac_f32_e32 v108, v111, v108
	v_div_fixup_f32 v65, v65, v64, 1.0
	v_div_fixup_f32 v71, v71, v70, 1.0
	v_div_fixup_f32 v77, v77, v76, 1.0
	v_div_fixup_f32 v83, v83, v82, 1.0
	v_mul_f32_e32 v65, v24, v65
	v_mul_f32_e32 v71, v25, v71
	v_mul_f32_e32 v77, v26, v77
	v_mul_f32_e32 v83, v27, v83
	v_mul_f32_e32 v65, v8, v65
	v_mul_f32_e32 v71, v9, v71
	v_mul_f32_e32 v77, v10, v77
	v_mul_f32_e32 v83, v11, v83
	v_cvt_pk_bf16_f32 v65, v65, v65
	v_cvt_pk_bf16_f32 v71, v71, v71
	v_cvt_pk_bf16_f32 v77, v77, v77
	v_cvt_pk_bf16_f32 v83, v83, v83
	ds_write_b16 v112, v65 offset:1024
	ds_write_b16 v112, v71 offset:1088
	ds_write_b16 v112, v77 offset:1152
	ds_write_b16 v112, v83 offset:1216
	v_div_scale_f32 v91, vcc, 1.0, v88, 1.0
	v_mul_f32_e32 v92, v91, v90
	v_fma_f32 v93, -v89, v92, v91
	v_fmac_f32_e32 v92, v93, v90
	v_fma_f32 v89, -v89, v92, v91
	v_div_fmas_f32 v89, v89, v90, v92
	v_div_scale_f32 v97, vcc, 1.0, v94, 1.0
	v_mul_f32_e32 v98, v97, v96
	v_fma_f32 v99, -v95, v98, v97
	v_fmac_f32_e32 v98, v99, v96
	v_fma_f32 v95, -v95, v98, v97
	v_div_fmas_f32 v95, v95, v96, v98
	v_div_scale_f32 v103, vcc, 1.0, v100, 1.0
	v_mul_f32_e32 v104, v103, v102
	v_fma_f32 v105, -v101, v104, v103
	v_fmac_f32_e32 v104, v105, v102
	v_fma_f32 v101, -v101, v104, v103
	v_div_fmas_f32 v101, v101, v102, v104
	v_div_scale_f32 v109, vcc, 1.0, v106, 1.0
	v_mul_f32_e32 v110, v109, v108
	v_fma_f32 v111, -v107, v110, v109
	v_fmac_f32_e32 v110, v111, v108
	v_fma_f32 v107, -v107, v110, v109
	v_div_fmas_f32 v107, v107, v108, v110
	v_div_fixup_f32 v89, v89, v88, 1.0
	v_div_fixup_f32 v95, v95, v94, 1.0
	v_div_fixup_f32 v101, v101, v100, 1.0
	v_div_fixup_f32 v107, v107, v106, 1.0
	v_mul_f32_e32 v89, v28, v89
	v_mul_f32_e32 v95, v29, v95
	v_mul_f32_e32 v101, v30, v101
	v_mul_f32_e32 v107, v31, v107
	v_mul_f32_e32 v89, v12, v89
	v_mul_f32_e32 v95, v13, v95
	v_mul_f32_e32 v101, v14, v101
	v_mul_f32_e32 v107, v15, v107
	v_cvt_pk_bf16_f32 v89, v89, v89
	v_cvt_pk_bf16_f32 v95, v95, v95
	v_cvt_pk_bf16_f32 v101, v101, v101
	v_cvt_pk_bf16_f32 v107, v107, v107
	ds_write_b16 v112, v89 offset:1536
	ds_write_b16 v112, v95 offset:1600
	ds_write_b16 v112, v101 offset:1664
	ds_write_b16 v112, v107 offset:1728
	ds_read_b128 v[120:123], v113
	ds_read_b128 v[124:127], v113 offset:1024
	s_waitcnt lgkmcnt(0)
	global_store_dwordx4 v114, v[120:123], s[98:99]
	s_add_u32 s98, s98, 0x16000
	s_addc_u32 s99, s99, 0
	global_store_dwordx4 v114, v[124:127], s[98:99]
	s_add_u32 s98, s98, 0x16000
	s_addc_u32 s99, s99, 0
	s_add_i32 s47, s47, s92
	s_cmpk_gt_i32 s47, 0x107f
	s_cbranch_scc1 .LBB0_2292
.LBB0_2284:
	s_and_b32 s4, s47, 7
	s_bfe_u32 s5, s47, 0x60003
	s_lshr_b32 s6, s47, 9
	s_lshl_b32 s6, s6, 6
	s_add_u32 s5, s5, s6
	s_mul_hi_u32 s6, s5, 0xaaaaaaab
	s_lshr_b32 s6, s6, 3
	s_mul_i32 s7, s6, 12
	s_sub_u32 s5, s5, s7
	s_mul_i32 s4, s4, 12
	s_add_u32 s4, s4, s5
	s_lshl_b32 s48, s4, 7
	s_lshl_b32 s49, s6, 7
	s_setprio 0
	v_lshl_or_b32 v64, v183, 3, v191
	v_and_b32_e32 v65, 63, v64
	v_lshrrev_b32_e32 v66, 3, v65
	v_lshrrev_b32_e32 v67, 4, v65
	v_xor_b32_e32 v67, v67, v65
	v_and_b32_e32 v67, 7, v67
	v_lshlrev_b32_e32 v67, 4, v67
	s_movk_i32 s99, 0x800
	v_mad_u32_u24 v112, v66, s99, v67
	v_xor_b32_e32 v68, 64, v112
	v_add_u32_e32 v113, 0x3c00, v68
	v_add_u32_e32 v114, 0x7800, v112
	v_add_u32_e32 v115, 0xb400, v68
	v_add_u32_e32 v116, 0x10000, v112
	v_add_u32_e32 v117, 0x13c00, v68
	v_add_u32_e32 v118, 0x17800, v112
	v_add_u32_e32 v119, 0x1b400, v68
	v_and_b32_e32 v69, 31, v64
	v_bfe_u32 v70, v64, 5, 1
	v_bfe_u32 v71, v64, 1, 3
	v_xor_b32_e32 v71, v71, v70
	v_lshlrev_b32_e32 v71, 4, v71
	v_bfe_u32 v72, v64, 7, 1
	v_lshl_or_b32 v72, v72, 6, v69
	v_lshl_add_u32 v120, v72, 7, v71
	v_bfe_u32 v73, v64, 6, 1
	v_lshl_or_b32 v73, v73, 6, v69
	v_lshl_add_u32 v124, v73, 7, v71
	v_add_u32_e32 v124, 0x4000, v124
	v_xor_b32_e32 v121, 32, v120
	v_xor_b32_e32 v125, 32, v124
	v_xor_b32_e32 v122, 64, v120
	v_xor_b32_e32 v126, 64, v124
	v_xor_b32_e32 v123, 96, v120
	v_xor_b32_e32 v127, 96, v124
	v_lshrrev_b32_e32 v74, 6, v64
	s_nop 0
	v_readfirstlane_b32 s100, v74
	s_nop 3
	s_lshl_b32 s98, s100, 13
	s_mov_b32 s101, 0x1640000
	s_mov_b32 s99, s49
	s_cmp_lt_u32 s100, 2
	s_cmov_b32 s101, 0xb171900
	s_cmov_b32 s99, s48
	s_and_b32 s100, s100, 1
	s_lshl_b32 s100, s100, 6
	s_add_u32 s99, s99, s100
	s_mul_i32 s99, s99, 0x800
	s_add_u32 s99, s99, s101
	s_add_u32 s4, s90, s99
	s_addc_u32 s5, s91, 0
	v_readlane_b32 s99, v251, 0
	s_cmp_lg_u32 s99, 0
	s_cbranch_scc1 .Lg6_pref
	s_add_u32 m0, s98, 0x0
	s_nop 0
	global_load_lds_dwordx4 v112, s[4:5] offset:0
	global_load_lds_dwordx4 v113, s[4:5] offset:1024
	global_load_lds_dwordx4 v114, s[4:5] offset:2048
	global_load_lds_dwordx4 v115, s[4:5] offset:3072
	s_add_u32 m0, s98, 0x1000
	s_nop 0
	global_load_lds_dwordx4 v116, s[4:5] offset:0
	global_load_lds_dwordx4 v117, s[4:5] offset:1024
	global_load_lds_dwordx4 v118, s[4:5] offset:2048
	global_load_lds_dwordx4 v119, s[4:5] offset:3072
	s_add_u32 s4, s4, 0x80
	s_addc_u32 s5, s5, 0
	s_add_u32 m0, s98, 0x8000
	s_nop 0
	global_load_lds_dwordx4 v112, s[4:5] offset:0
	global_load_lds_dwordx4 v113, s[4:5] offset:1024
	global_load_lds_dwordx4 v114, s[4:5] offset:2048
	global_load_lds_dwordx4 v115, s[4:5] offset:3072
	s_add_u32 m0, s98, 0x9000
	s_nop 0
	global_load_lds_dwordx4 v116, s[4:5] offset:0
	global_load_lds_dwordx4 v117, s[4:5] offset:1024
	global_load_lds_dwordx4 v118, s[4:5] offset:2048
	global_load_lds_dwordx4 v119, s[4:5] offset:3072
	s_add_u32 s4, s4, 0x80
	s_addc_u32 s5, s5, 0
	s_mov_b32 s101, 0
	s_branch .Lg6_prol

.LBB0_2348:
	s_cmp_ge_i32 s33, s72
	s_cselect_b64 s[26:27], -1, 0
	s_sub_i32 s2, s33, s72
	s_and_b32 s3, 1, s2
	s_lshr_b32 s2, s2, 1
	s_add_i32 s2, s2, s72
	s_cmp_eq_u32 s3, 1
	s_cselect_b32 s3, 0x580, 0
	s_cmp_lt_i32 s33, s72
	s_cselect_b32 s2, s33, s2
	s_mul_hi_i32 s4, s2, 0x2aaaaaab
	s_cselect_b32 s6, 44, 22
	s_cselect_b32 s3, 0, s3
	s_lshr_b32 s5, s4, 31
	s_ashr_i32 s4, s4, 4
	s_add_i32 s4, s4, s5
	s_mul_i32 s5, s4, 0x60
	s_sub_i32 s2, s2, s5
	s_lshl_b32 s7, s2, 7
	s_lshl_b32 s18, s3, 1
	s_lshl_b32 s8, s4, 7
	s_setprio 0
	v_lshl_or_b32 v64, v183, 3, v191
	v_and_b32_e32 v65, 63, v64
	v_lshrrev_b32_e32 v66, 3, v65
	v_lshrrev_b32_e32 v67, 4, v65
	v_xor_b32_e32 v67, v67, v65
	v_and_b32_e32 v67, 7, v67
	v_lshlrev_b32_e32 v67, 4, v67
	s_movk_i32 s99, 0x1600
	v_mad_u32_u24 v112, v66, s99, v67
	v_xor_b32_e32 v68, 64, v112
	v_add_u32_e32 v113, 0xac00, v68
	v_add_u32_e32 v114, 0x15800, v112
	v_add_u32_e32 v115, 0x20400, v68
	v_add_u32_e32 v116, 0x2c000, v112
	v_add_u32_e32 v117, 0x36c00, v68
	v_add_u32_e32 v118, 0x41800, v112
	v_add_u32_e32 v119, 0x4c400, v68
	v_and_b32_e32 v69, 31, v64
	v_bfe_u32 v70, v64, 5, 1
	v_bfe_u32 v71, v64, 1, 3
	v_xor_b32_e32 v71, v71, v70
	v_lshlrev_b32_e32 v71, 4, v71
	v_bfe_u32 v72, v64, 7, 1
	v_lshl_or_b32 v72, v72, 6, v69
	v_lshl_add_u32 v120, v72, 7, v71
	v_bfe_u32 v73, v64, 6, 1
	v_lshl_or_b32 v73, v73, 6, v69
	v_lshl_add_u32 v124, v73, 7, v71
	v_add_u32_e32 v124, 0x4000, v124
	v_xor_b32_e32 v121, 32, v120
	v_xor_b32_e32 v125, 32, v124
	v_xor_b32_e32 v122, 64, v120
	v_xor_b32_e32 v126, 64, v124
	v_xor_b32_e32 v123, 96, v120
	v_xor_b32_e32 v127, 96, v124
	v_lshrrev_b32_e32 v74, 6, v64
	s_nop 0
	v_readfirstlane_b32 s100, v74
	s_nop 3
	s_lshl_b32 s98, s100, 13
	s_mov_b32 s101, 0x26c0000
	s_mov_b32 s99, s8
	s_cmp_lt_u32 s100, 2
	s_cmov_b32 s101, 0x3971900
	s_cmov_b32 s99, s7
	s_and_b32 s100, s100, 1
	s_lshl_b32 s100, s100, 6
	s_add_u32 s99, s99, s100
	s_mul_i32 s99, s99, 0x1600
	s_add_u32 s99, s99, s101
	s_add_u32 s99, s99, s18
	s_add_u32 s2, s90, s99
	s_addc_u32 s3, s91, 0
	s_add_u32 m0, s98, 0x0
	s_nop 0
	global_load_lds_dwordx4 v112, s[2:3] offset:0
	global_load_lds_dwordx4 v113, s[2:3] offset:1024
	global_load_lds_dwordx4 v114, s[2:3] offset:2048
	global_load_lds_dwordx4 v115, s[2:3] offset:3072
	s_add_u32 m0, s98, 0x1000
	s_nop 0
	global_load_lds_dwordx4 v116, s[2:3] offset:0
	global_load_lds_dwordx4 v117, s[2:3] offset:1024
	global_load_lds_dwordx4 v118, s[2:3] offset:2048
	global_load_lds_dwordx4 v119, s[2:3] offset:3072
	s_add_u32 s2, s2, 0x80
	s_addc_u32 s3, s3, 0
	s_add_u32 m0, s98, 0x8000
	s_nop 0
	global_load_lds_dwordx4 v112, s[2:3] offset:0
	global_load_lds_dwordx4 v113, s[2:3] offset:1024
	global_load_lds_dwordx4 v114, s[2:3] offset:2048
	global_load_lds_dwordx4 v115, s[2:3] offset:3072
	s_add_u32 m0, s98, 0x9000
	s_nop 0
	global_load_lds_dwordx4 v116, s[2:3] offset:0
	global_load_lds_dwordx4 v117, s[2:3] offset:1024
	global_load_lds_dwordx4 v118, s[2:3] offset:2048
	global_load_lds_dwordx4 v119, s[2:3] offset:3072
	s_add_u32 s2, s2, 0x80
	s_addc_u32 s3, s3, 0
	v_mov_b32_e32 v48, 0
	v_mov_b32_e32 v49, 0
	v_mov_b32_e32 v50, 0
	v_mov_b32_e32 v51, 0
	v_mov_b32_e32 v52, 0
	v_mov_b32_e32 v53, 0
	v_mov_b32_e32 v54, 0
	v_mov_b32_e32 v55, 0
	v_mov_b32_e32 v56, 0
	v_mov_b32_e32 v57, 0
	v_mov_b32_e32 v58, 0
	v_mov_b32_e32 v59, 0
	v_mov_b32_e32 v60, 0
	v_mov_b32_e32 v61, 0
	v_mov_b32_e32 v62, 0
	v_mov_b32_e32 v63, 0
	v_mov_b32_e32 v16, 0
	v_mov_b32_e32 v17, 0
	v_mov_b32_e32 v18, 0
	v_mov_b32_e32 v19, 0
	v_mov_b32_e32 v20, 0
	v_mov_b32_e32 v21, 0
	v_mov_b32_e32 v22, 0
	v_mov_b32_e32 v23, 0
	v_mov_b32_e32 v24, 0
	v_mov_b32_e32 v25, 0
	v_mov_b32_e32 v26, 0
	v_mov_b32_e32 v27, 0
	v_mov_b32_e32 v28, 0
	v_mov_b32_e32 v29, 0
	v_mov_b32_e32 v30, 0
	v_mov_b32_e32 v31, 0
	v_mov_b32_e32 v32, 0
	v_mov_b32_e32 v33, 0
	v_mov_b32_e32 v34, 0
	v_mov_b32_e32 v35, 0
	v_mov_b32_e32 v36, 0
	v_mov_b32_e32 v37, 0
	v_mov_b32_e32 v38, 0
	v_mov_b32_e32 v39, 0
	v_mov_b32_e32 v40, 0
	v_mov_b32_e32 v41, 0
	v_mov_b32_e32 v42, 0
	v_mov_b32_e32 v43, 0
	v_mov_b32_e32 v44, 0
	v_mov_b32_e32 v45, 0
	v_mov_b32_e32 v46, 0
	v_mov_b32_e32 v47, 0
	v_mov_b32_e32 v0, 0
	v_mov_b32_e32 v1, 0
	v_mov_b32_e32 v2, 0
	v_mov_b32_e32 v3, 0
	v_mov_b32_e32 v4, 0
	v_mov_b32_e32 v5, 0
	v_mov_b32_e32 v6, 0
	v_mov_b32_e32 v7, 0
	v_mov_b32_e32 v8, 0
	v_mov_b32_e32 v9, 0
	v_mov_b32_e32 v10, 0
	v_mov_b32_e32 v11, 0
	v_mov_b32_e32 v12, 0
	v_mov_b32_e32 v13, 0
	v_mov_b32_e32 v14, 0
	v_mov_b32_e32 v15, 0
	s_lshr_b32 s5, s6, 1
	s_sub_u32 s5, s5, 1
	s_waitcnt vmcnt(8)
